# EpiResid: second-half residual loads issued with the first half (counted vmcnt), split-K read-back pipelined 8 deep, row-sum atomics deferred to the epilogue end
# speedup vs baseline: 1.0306x; 1.0134x over previous
; template <class Epi>
; __device__ __forceinline__ void gemm_phase(LAS unsigned char* lds, const Gemm g, const StaticOrder& S, const Epi& E) {
;     ...
;                 for (int sl = 0; sl < S.NS; ++sl) { if (sl == myslice) continue;
;                     const __amdgpu_buffer_rsrc_t qrs = __builtin_amdgcn_make_buffer_rsrc((void*)(T + (size_t)sl * 65536), 0, 262144, 0x00020000);
; #pragma unroll
;                     for (int a = 0; a < 2; ++a)
; #pragma unroll
;                         for (int m = 0; m < 4; ++m)
; #pragma unroll
;                             for (int b = 0; b < 2; ++b)
; #pragma unroll
;                                 for (int n = 0; n < 2; ++n) acc[a][b][m][n] += __builtin_bit_cast(f32x4, __builtin_amdgcn_raw_buffer_load_b128(qrs, (int)(toff + (((a * 4 + m) * 2 + b) * 2 + n) * 8192), 0, 16)); }
.LBB0_303:
	s_lshl_b32 s10, s16, 18
	s_add_u32 s20, s43, s10
	s_addc_u32 s10, s97, 0
	s_and_b32 s21, s10, 0xffff
	buffer_load_dwordx4 v[196:199], v133, s[20:23], 0 offen sc1
	buffer_load_dwordx4 v[200:203], v152, s[20:23], 0 offen sc1
	buffer_load_dwordx4 v[204:207], v156, s[20:23], 0 offen sc1
	buffer_load_dwordx4 v[208:211], v157, s[20:23], 0 offen sc1
	buffer_load_dwordx4 v[212:215], v160, s[20:23], 0 offen sc1
	buffer_load_dwordx4 v[216:219], v161, s[20:23], 0 offen sc1
	buffer_load_dwordx4 v[220:223], v162, s[20:23], 0 offen sc1
	buffer_load_dwordx4 v[224:227], v163, s[20:23], 0 offen sc1
	s_waitcnt vmcnt(7)
	v_pk_add_f32 v[130:131], v[130:131], v[198:199]
	v_pk_add_f32 v[128:129], v[128:129], v[196:197]
	buffer_load_dwordx4 v[196:199], v164, s[20:23], 0 offen sc1
	s_waitcnt vmcnt(7)
	v_pk_add_f32 v[126:127], v[126:127], v[202:203]
	v_pk_add_f32 v[124:125], v[124:125], v[200:201]
	buffer_load_dwordx4 v[200:203], v165, s[20:23], 0 offen sc1
	s_waitcnt vmcnt(7)
	v_pk_add_f32 v[122:123], v[122:123], v[206:207]
	v_pk_add_f32 v[120:121], v[120:121], v[204:205]
	buffer_load_dwordx4 v[204:207], v166, s[20:23], 0 offen sc1
	s_waitcnt vmcnt(7)
	v_pk_add_f32 v[118:119], v[118:119], v[210:211]
	v_pk_add_f32 v[116:117], v[116:117], v[208:209]
	buffer_load_dwordx4 v[208:211], v167, s[20:23], 0 offen sc1
	s_waitcnt vmcnt(7)
	v_pk_add_f32 v[114:115], v[114:115], v[214:215]
	v_pk_add_f32 v[112:113], v[112:113], v[212:213]
	buffer_load_dwordx4 v[212:215], v168, s[20:23], 0 offen sc1
	s_waitcnt vmcnt(7)
	v_pk_add_f32 v[110:111], v[110:111], v[218:219]
	v_pk_add_f32 v[108:109], v[108:109], v[216:217]
	buffer_load_dwordx4 v[216:219], v169, s[20:23], 0 offen sc1
	s_waitcnt vmcnt(7)
	v_pk_add_f32 v[106:107], v[106:107], v[222:223]
	v_pk_add_f32 v[104:105], v[104:105], v[220:221]
	buffer_load_dwordx4 v[220:223], v170, s[20:23], 0 offen sc1
	s_waitcnt vmcnt(7)
	v_pk_add_f32 v[102:103], v[102:103], v[226:227]
	v_pk_add_f32 v[100:101], v[100:101], v[224:225]
	buffer_load_dwordx4 v[224:227], v171, s[20:23], 0 offen sc1
	s_waitcnt vmcnt(7)
	v_pk_add_f32 v[98:99], v[98:99], v[198:199]
	v_pk_add_f32 v[96:97], v[96:97], v[196:197]
	buffer_load_dwordx4 v[196:199], v172, s[20:23], 0 offen sc1
	s_waitcnt vmcnt(7)
	v_pk_add_f32 v[94:95], v[94:95], v[202:203]
	v_pk_add_f32 v[92:93], v[92:93], v[200:201]
	buffer_load_dwordx4 v[200:203], v173, s[20:23], 0 offen sc1
	s_waitcnt vmcnt(7)
	v_pk_add_f32 v[90:91], v[90:91], v[206:207]
	v_pk_add_f32 v[88:89], v[88:89], v[204:205]
	buffer_load_dwordx4 v[204:207], v174, s[20:23], 0 offen sc1
	s_waitcnt vmcnt(7)
	v_pk_add_f32 v[86:87], v[86:87], v[210:211]
	v_pk_add_f32 v[84:85], v[84:85], v[208:209]
	buffer_load_dwordx4 v[208:211], v175, s[20:23], 0 offen sc1
	s_waitcnt vmcnt(7)
	v_pk_add_f32 v[82:83], v[82:83], v[214:215]
	v_pk_add_f32 v[80:81], v[80:81], v[212:213]
	buffer_load_dwordx4 v[212:215], v176, s[20:23], 0 offen sc1
	s_waitcnt vmcnt(7)
	v_pk_add_f32 v[78:79], v[78:79], v[218:219]
	v_pk_add_f32 v[76:77], v[76:77], v[216:217]
	buffer_load_dwordx4 v[216:219], v177, s[20:23], 0 offen sc1
	s_waitcnt vmcnt(7)
	v_pk_add_f32 v[74:75], v[74:75], v[222:223]
	v_pk_add_f32 v[72:73], v[72:73], v[220:221]
	buffer_load_dwordx4 v[220:223], v178, s[20:23], 0 offen sc1
	s_waitcnt vmcnt(7)
	v_pk_add_f32 v[70:71], v[70:71], v[226:227]
	v_pk_add_f32 v[68:69], v[68:69], v[224:225]
	buffer_load_dwordx4 v[224:227], v179, s[20:23], 0 offen sc1
	s_waitcnt vmcnt(7)
	v_pk_add_f32 v[66:67], v[66:67], v[198:199]
	v_pk_add_f32 v[64:65], v[64:65], v[196:197]
	buffer_load_dwordx4 v[196:199], v180, s[20:23], 0 offen sc1
	s_waitcnt vmcnt(7)
	v_pk_add_f32 v[62:63], v[62:63], v[202:203]
	v_pk_add_f32 v[60:61], v[60:61], v[200:201]
	buffer_load_dwordx4 v[200:203], v181, s[20:23], 0 offen sc1
	s_waitcnt vmcnt(7)
	v_pk_add_f32 v[58:59], v[58:59], v[206:207]
	v_pk_add_f32 v[56:57], v[56:57], v[204:205]
	buffer_load_dwordx4 v[204:207], v182, s[20:23], 0 offen sc1
	s_waitcnt vmcnt(7)
	v_pk_add_f32 v[54:55], v[54:55], v[210:211]
	v_pk_add_f32 v[52:53], v[52:53], v[208:209]
	buffer_load_dwordx4 v[208:211], v183, s[20:23], 0 offen sc1
	s_waitcnt vmcnt(7)
	v_pk_add_f32 v[50:51], v[50:51], v[214:215]
	v_pk_add_f32 v[48:49], v[48:49], v[212:213]
	buffer_load_dwordx4 v[212:215], v184, s[20:23], 0 offen sc1
	s_waitcnt vmcnt(7)
	v_pk_add_f32 v[46:47], v[46:47], v[218:219]
	v_pk_add_f32 v[44:45], v[44:45], v[216:217]
	buffer_load_dwordx4 v[216:219], v185, s[20:23], 0 offen sc1
	s_waitcnt vmcnt(7)
	v_pk_add_f32 v[42:43], v[42:43], v[222:223]
	v_pk_add_f32 v[40:41], v[40:41], v[220:221]
	buffer_load_dwordx4 v[220:223], v186, s[20:23], 0 offen sc1
	s_waitcnt vmcnt(7)
	v_pk_add_f32 v[38:39], v[38:39], v[226:227]
	v_pk_add_f32 v[36:37], v[36:37], v[224:225]
	buffer_load_dwordx4 v[224:227], v187, s[20:23], 0 offen sc1
	s_waitcnt vmcnt(7)
	v_pk_add_f32 v[34:35], v[34:35], v[198:199]
	v_pk_add_f32 v[32:33], v[32:33], v[196:197]
	s_waitcnt vmcnt(6)
	v_pk_add_f32 v[30:31], v[30:31], v[202:203]
	v_pk_add_f32 v[28:29], v[28:29], v[200:201]
	s_waitcnt vmcnt(5)
	v_pk_add_f32 v[26:27], v[26:27], v[206:207]
	v_pk_add_f32 v[24:25], v[24:25], v[204:205]
	s_waitcnt vmcnt(4)
	v_pk_add_f32 v[22:23], v[22:23], v[210:211]
	v_pk_add_f32 v[20:21], v[20:21], v[208:209]
	s_waitcnt vmcnt(3)
	v_pk_add_f32 v[18:19], v[18:19], v[214:215]
	v_pk_add_f32 v[16:17], v[16:17], v[212:213]
	s_waitcnt vmcnt(2)
	v_pk_add_f32 v[14:15], v[14:15], v[218:219]
	v_pk_add_f32 v[12:13], v[12:13], v[216:217]
	s_waitcnt vmcnt(1)
	v_pk_add_f32 v[10:11], v[10:11], v[222:223]
	v_pk_add_f32 v[8:9], v[8:9], v[220:221]
	s_waitcnt vmcnt(0)
	v_pk_add_f32 v[6:7], v[6:7], v[226:227]
	v_pk_add_f32 v[4:5], v[4:5], v[224:225]

; __device__ __forceinline__ u32x4 pack8(f32x4 a, f32x4 b) { u32x4 w; w.x = pk2(a[0], a[1]); w.y = pk2(a[2], a[3]); w.z = pk2(b[0], b[1]); w.w = pk2(b[2], b[3]); return w; }
; __device__ __forceinline__ float dot8(f32x4 a, f32x4 b) { return (a[0] * a[0] + a[1] * a[1]) + (a[2] * a[2] + a[3] * a[3]) + (b[0] * b[0] + b[1] * b[1]) + (b[2] * b[2] + b[3] * b[3]); }
; __device__ __forceinline__ float red_fq(float s) { s += __shfl_xor(s, 16); s += __shfl_xor(s, 32); return s; }
;     __device__ __forceinline__ void operator()(AccRef acc, const Unit& u, int wr, int wc, int fr, int fq) const {
;     ...
;             const float* rp = (row < MP) ? res0 + (size_t)row * DM : res1 + (size_t)(row - MP) * DM;
;             float s = 0.f;
;             _Pragma("unroll") for (int bj = 0; bj < 2; ++bj) { const int col = col0 + bj * 128;
;                 f32x4 v0 = *(const f32x4*)(rp + col) + acc[ai][bj][m][0] * scale, v1 = *(const f32x4*)(rp + col + 4) + acc[ai][bj][m][1] * scale;
;                 *(f32x4*)(out + (size_t)row * DM + col) = v0; *(f32x4*)(out + (size_t)row * DM + col + 4) = v1;
;                 if (WB) *(u32x4*)(ob + (size_t)row * DM + col) = pack8(v0, v1);
;                 s += dot8(v0, v1); }
;             s = red_fq(s); if (fq == 0) unsafeAtomicAdd(ss + row, s);
.LBB0_312:
	v_lshl_add_u32 v144, s96, 8, v155
	v_cmp_lt_i32_e32 vcc, s91, v144
	s_and_saveexec_b64 s[16:17], vcc
	s_xor_b64 s[16:17], exec, s[16:17]
	v_add_u32_e32 v138, 0xffff8000, v144
	v_mov_b32_e32 v139, v2
	v_lshlrev_b64 v[138:139], 12, v[138:139]
	v_lshl_add_u64 v[148:149], s[38:39], 0, v[138:139]
	v_mov_b32_e32 v145, v2
	s_andn2_saveexec_b64 s[16:17], s[16:17]
	v_ashrrev_i32_e32 v145, 31, v144
	v_lshlrev_b64 v[138:139], 12, v[144:145]
	v_lshl_add_u64 v[148:149], s[36:37], 0, v[138:139]
	s_or_b64 exec, exec, s[16:17]
	v_and_b32_e32 v138, 64, v193
	v_lshl_or_b32 v142, s95, 8, v188
	v_xor_b32_e32 v3, 16, v193
	v_add_u32_e32 v138, 64, v138
	v_cmp_lt_i32_e32 vcc, v3, v138
	v_ashrrev_i32_e32 v143, 31, v142
	v_lshlrev_b64 v[146:147], 2, v[142:143]
	v_cndmask_b32_e32 v3, v193, v3, vcc
	v_lshlrev_b32_e32 v195, 2, v3
	v_xor_b32_e32 v3, 32, v193
	v_lshl_add_u64 v[148:149], v[148:149], 0, v[146:147]
	v_cmp_lt_i32_e32 vcc, v3, v138
	global_load_dwordx4 v[138:141], v[148:149], off offset:16
	global_load_dwordx4 v[196:199], v[148:149], off
	global_load_dwordx4 v[216:219], v[148:149], off offset:528
	global_load_dwordx4 v[220:223], v[148:149], off offset:512
	v_cndmask_b32_e32 v3, v193, v3, vcc
	v_lshlrev_b32_e32 v3, 2, v3
	s_waitcnt vmcnt(3)
	v_pk_fma_f32 v[140:141], v[126:127], 0.5, v[140:141] op_sel_hi:[1,0,1]
	v_lshlrev_b64 v[126:127], 11, v[144:145]
	s_waitcnt vmcnt(2)
	v_pk_fma_f32 v[130:131], v[130:131], 0.5, v[198:199] op_sel_hi:[1,0,1]
	v_pk_fma_f32 v[128:129], v[128:129], 0.5, v[196:197] op_sel_hi:[1,0,1]
	v_lshl_add_u64 v[126:127], s[18:19], 0, v[126:127]
	v_lshl_add_u64 v[200:201], v[142:143], 1, v[126:127]
	v_mul_f32_e32 v126, v129, v129
	v_mul_f32_e32 v127, v131, v131
	v_pk_fma_f32 v[138:139], v[124:125], 0.5, v[138:139] op_sel_hi:[1,0,1]
	v_fmac_f32_e32 v126, v128, v128
	v_fmac_f32_e32 v127, v130, v130
	v_lshlrev_b64 v[124:125], 12, v[144:145]
	v_add_f32_e32 v126, v126, v127
	v_mul_f32_e32 v127, v139, v139
	v_lshl_add_u64 v[124:125], s[30:31], 0, v[124:125]
	v_fmac_f32_e32 v127, v138, v138
	v_lshl_add_u64 v[124:125], v[124:125], 0, v[146:147]
	v_cvt_pk_bf16_f32 v196, v128, v129
	v_cvt_pk_bf16_f32 v197, v130, v131
	v_cvt_pk_bf16_f32 v198, v138, v139
	v_cvt_pk_bf16_f32 v199, v140, v141
	v_add_f32_e32 v126, v127, v126
	v_mul_f32_e32 v127, v141, v141
	global_store_dwordx4 v[124:125], v[128:131], off
	global_store_dwordx4 v[124:125], v[138:141], off offset:16
	global_store_dwordx4 v[200:201], v[196:199], off
	v_fmac_f32_e32 v127, v140, v140
	v_add_f32_e32 v130, v127, v126
	s_nop 0
	s_nop 0
	s_waitcnt vmcnt(4)
	v_pk_fma_f32 v[118:119], v[118:119], 0.5, v[218:219] op_sel_hi:[1,0,1]
	s_waitcnt vmcnt(3)
	v_pk_fma_f32 v[122:123], v[122:123], 0.5, v[222:223] op_sel_hi:[1,0,1]
	v_pk_fma_f32 v[120:121], v[120:121], 0.5, v[220:221] op_sel_hi:[1,0,1]
	v_pk_fma_f32 v[116:117], v[116:117], 0.5, v[216:217] op_sel_hi:[1,0,1]
	global_store_dwordx4 v[124:125], v[120:123], off offset:512
	global_store_dwordx4 v[124:125], v[116:119], off offset:528
	v_cvt_pk_bf16_f32 v124, v120, v121
	v_mul_f32_e32 v121, v121, v121
	v_fmac_f32_e32 v121, v120, v120
	v_mul_f32_e32 v120, v123, v123
	v_cvt_pk_bf16_f32 v126, v116, v117
	v_fmac_f32_e32 v120, v122, v122
	v_mul_f32_e32 v117, v117, v117
	v_add_f32_e32 v120, v121, v120
	v_fmac_f32_e32 v117, v116, v116
	v_add_f32_e32 v116, v117, v120
	v_mul_f32_e32 v117, v119, v119
	v_fmac_f32_e32 v117, v118, v118
	v_add_f32_e32 v116, v117, v116
	v_add_f32_e32 v116, v130, v116
	ds_bpermute_b32 v117, v195, v116
	v_cvt_pk_bf16_f32 v125, v122, v123
	v_cvt_pk_bf16_f32 v127, v118, v119
	global_store_dwordx4 v[200:201], v[124:127], off offset:256
	s_waitcnt lgkmcnt(0)
	v_add_f32_e32 v116, v116, v117
	ds_bpermute_b32 v117, v3, v116
	s_and_saveexec_b64 s[16:17], s[6:7]
	s_cbranch_execz .LBB0_318
	s_waitcnt lgkmcnt(0)
	v_add_f32_e32 v118, v116, v117
	v_lshl_add_u64 v[116:117], v[144:145], 2, s[84:85]
	v_mov_b32_e32 v224, v116
	v_mov_b32_e32 v225, v117
	v_mov_b32_e32 v226, v118
.LBB0_318:
	s_or_b64 exec, exec, s[16:17]
	s_waitcnt lgkmcnt(0)
	v_or_b32_e32 v116, 16, v144
	v_cmp_lt_i32_e32 vcc, s91, v116
	s_and_saveexec_b64 s[16:17], vcc
	s_xor_b64 s[16:17], exec, s[16:17]
	v_add_u32_e32 v118, 0xffff8010, v144
	v_mov_b32_e32 v119, v2
	v_lshlrev_b64 v[118:119], 12, v[118:119]
	v_lshl_add_u64 v[118:119], s[38:39], 0, v[118:119]
	v_mov_b32_e32 v117, v2
	s_andn2_saveexec_b64 s[16:17], s[16:17]
	v_ashrrev_i32_e32 v117, 31, v116
	v_lshlrev_b64 v[118:119], 12, v[116:117]
	v_lshl_add_u64 v[118:119], s[36:37], 0, v[118:119]
	s_or_b64 exec, exec, s[16:17]
	v_lshl_add_u64 v[126:127], v[118:119], 0, v[146:147]
	global_load_dwordx4 v[118:121], v[126:127], off offset:16
	global_load_dwordx4 v[122:125], v[126:127], off
	global_load_dwordx4 v[216:219], v[126:127], off offset:528
	global_load_dwordx4 v[220:223], v[126:127], off offset:512
	s_waitcnt vmcnt(3)
	v_pk_fma_f32 v[108:109], v[108:109], 0.5, v[118:119] op_sel_hi:[1,0,1]
	v_lshlrev_b64 v[118:119], 12, v[116:117]
	v_lshl_add_u64 v[118:119], s[30:31], 0, v[118:119]
	s_waitcnt vmcnt(2)
	v_pk_fma_f32 v[114:115], v[114:115], 0.5, v[124:125] op_sel_hi:[1,0,1]
	v_pk_fma_f32 v[112:113], v[112:113], 0.5, v[122:123] op_sel_hi:[1,0,1]
	v_lshl_add_u64 v[122:123], v[118:119], 0, v[146:147]
	v_pk_fma_f32 v[110:111], v[110:111], 0.5, v[120:121] op_sel_hi:[1,0,1]
	global_store_dwordx4 v[122:123], v[112:115], off
	global_store_dwordx4 v[122:123], v[108:111], off offset:16
	v_cvt_pk_bf16_f32 v118, v112, v113
	v_mul_f32_e32 v113, v113, v113
	v_fmac_f32_e32 v113, v112, v112
	v_mul_f32_e32 v112, v115, v115
	v_cvt_pk_bf16_f32 v120, v108, v109
	v_lshlrev_b64 v[124:125], 11, v[116:117]
	v_fmac_f32_e32 v112, v114, v114
	v_mul_f32_e32 v109, v109, v109
	v_lshl_add_u64 v[124:125], s[18:19], 0, v[124:125]
	v_add_f32_e32 v112, v113, v112
	v_fmac_f32_e32 v109, v108, v108
	v_cvt_pk_bf16_f32 v119, v114, v115
	v_cvt_pk_bf16_f32 v121, v110, v111
	v_lshl_add_u64 v[124:125], v[142:143], 1, v[124:125]
	v_add_f32_e32 v108, v109, v112
	v_mul_f32_e32 v109, v111, v111
	global_store_dwordx4 v[124:125], v[118:121], off
	v_fmac_f32_e32 v109, v110, v110
	s_nop 0
	v_add_f32_e32 v118, v109, v108
	s_nop 0
	s_nop 0
	s_waitcnt vmcnt(4)
; __device__ __forceinline__ u32x4 pack8(f32x4 a, f32x4 b) { u32x4 w; w.x = pk2(a[0], a[1]); w.y = pk2(a[2], a[3]); w.z = pk2(b[0], b[1]); w.w = pk2(b[2], b[3]); return w; }
; __device__ __forceinline__ float dot8(f32x4 a, f32x4 b) { return (a[0] * a[0] + a[1] * a[1]) + (a[2] * a[2] + a[3] * a[3]) + (b[0] * b[0] + b[1] * b[1]) + (b[2] * b[2] + b[3] * b[3]); }
; __device__ __forceinline__ float red_fq(float s) { s += __shfl_xor(s, 16); s += __shfl_xor(s, 32); return s; }
;     __device__ __forceinline__ void operator()(AccRef acc, const Unit& u, int wr, int wc, int fr, int fq) const {
;     ...
;             const float* rp = (row < MP) ? res0 + (size_t)row * DM : res1 + (size_t)(row - MP) * DM;
;             float s = 0.f;
;             _Pragma("unroll") for (int bj = 0; bj < 2; ++bj) { const int col = col0 + bj * 128;
;                 f32x4 v0 = *(const f32x4*)(rp + col) + acc[ai][bj][m][0] * scale, v1 = *(const f32x4*)(rp + col + 4) + acc[ai][bj][m][1] * scale;
;                 *(f32x4*)(out + (size_t)row * DM + col) = v0; *(f32x4*)(out + (size_t)row * DM + col + 4) = v1;
;                 if (WB) *(u32x4*)(ob + (size_t)row * DM + col) = pack8(v0, v1);
;                 s += dot8(v0, v1); }
;             s = red_fq(s); if (fq == 0) unsafeAtomicAdd(ss + row, s);
	v_pk_fma_f32 v[102:103], v[102:103], 0.5, v[218:219] op_sel_hi:[1,0,1]
	s_waitcnt vmcnt(3)
	v_pk_fma_f32 v[106:107], v[106:107], 0.5, v[222:223] op_sel_hi:[1,0,1]
	v_pk_fma_f32 v[104:105], v[104:105], 0.5, v[220:221] op_sel_hi:[1,0,1]
	v_pk_fma_f32 v[100:101], v[100:101], 0.5, v[216:217] op_sel_hi:[1,0,1]
	global_store_dwordx4 v[122:123], v[104:107], off offset:512
	global_store_dwordx4 v[122:123], v[100:103], off offset:528
	v_cvt_pk_bf16_f32 v108, v104, v105
	v_mul_f32_e32 v105, v105, v105
	v_fmac_f32_e32 v105, v104, v104
	v_mul_f32_e32 v104, v107, v107
	v_cvt_pk_bf16_f32 v110, v100, v101
	v_fmac_f32_e32 v104, v106, v106
	v_mul_f32_e32 v101, v101, v101
	v_add_f32_e32 v104, v105, v104
	v_fmac_f32_e32 v101, v100, v100
	v_add_f32_e32 v100, v101, v104
	v_mul_f32_e32 v101, v103, v103
	v_fmac_f32_e32 v101, v102, v102
	v_add_f32_e32 v100, v101, v100
	v_add_f32_e32 v100, v118, v100
	ds_bpermute_b32 v101, v195, v100
	v_cvt_pk_bf16_f32 v109, v106, v107
	v_cvt_pk_bf16_f32 v111, v102, v103
	global_store_dwordx4 v[124:125], v[108:111], off offset:256
	s_waitcnt lgkmcnt(0)
	v_add_f32_e32 v100, v100, v101
	ds_bpermute_b32 v101, v3, v100
	s_and_saveexec_b64 s[16:17], s[6:7]
	s_cbranch_execz .LBB0_324
	s_waitcnt lgkmcnt(0)
	v_add_f32_e32 v102, v100, v101
	v_lshl_add_u64 v[100:101], v[116:117], 2, s[84:85]
	v_mov_b32_e32 v228, v100
	v_mov_b32_e32 v229, v101
	v_mov_b32_e32 v230, v102
.LBB0_324:
	s_or_b64 exec, exec, s[16:17]
	s_waitcnt lgkmcnt(0)
	v_or_b32_e32 v100, 32, v144
	v_cmp_lt_i32_e32 vcc, s91, v100
	s_and_saveexec_b64 s[16:17], vcc
	s_xor_b64 s[16:17], exec, s[16:17]
	v_add_u32_e32 v102, 0xffff8020, v144
	v_mov_b32_e32 v103, v2
	v_lshlrev_b64 v[102:103], 12, v[102:103]
	v_lshl_add_u64 v[102:103], s[38:39], 0, v[102:103]
	v_mov_b32_e32 v101, v2
	s_andn2_saveexec_b64 s[16:17], s[16:17]
	v_ashrrev_i32_e32 v101, 31, v100
	v_lshlrev_b64 v[102:103], 12, v[100:101]
	v_lshl_add_u64 v[102:103], s[36:37], 0, v[102:103]
	s_or_b64 exec, exec, s[16:17]
	v_lshl_add_u64 v[110:111], v[102:103], 0, v[146:147]
	global_load_dwordx4 v[102:105], v[110:111], off offset:16
	global_load_dwordx4 v[106:109], v[110:111], off
	global_load_dwordx4 v[216:219], v[110:111], off offset:528
	global_load_dwordx4 v[220:223], v[110:111], off offset:512
	s_waitcnt vmcnt(3)
	v_pk_fma_f32 v[92:93], v[92:93], 0.5, v[102:103] op_sel_hi:[1,0,1]
	v_lshlrev_b64 v[102:103], 12, v[100:101]
	v_lshl_add_u64 v[102:103], s[30:31], 0, v[102:103]
	s_waitcnt vmcnt(2)
	v_pk_fma_f32 v[98:99], v[98:99], 0.5, v[108:109] op_sel_hi:[1,0,1]
	v_pk_fma_f32 v[96:97], v[96:97], 0.5, v[106:107] op_sel_hi:[1,0,1]
	v_lshl_add_u64 v[106:107], v[102:103], 0, v[146:147]
	v_pk_fma_f32 v[94:95], v[94:95], 0.5, v[104:105] op_sel_hi:[1,0,1]
	global_store_dwordx4 v[106:107], v[96:99], off
	global_store_dwordx4 v[106:107], v[92:95], off offset:16
	v_cvt_pk_bf16_f32 v102, v96, v97
	v_mul_f32_e32 v97, v97, v97
	v_fmac_f32_e32 v97, v96, v96
	v_mul_f32_e32 v96, v99, v99
	v_cvt_pk_bf16_f32 v104, v92, v93
	v_lshlrev_b64 v[108:109], 11, v[100:101]
	v_fmac_f32_e32 v96, v98, v98
	v_mul_f32_e32 v93, v93, v93
	v_lshl_add_u64 v[108:109], s[18:19], 0, v[108:109]
	v_add_f32_e32 v96, v97, v96
	v_fmac_f32_e32 v93, v92, v92
	v_cvt_pk_bf16_f32 v103, v98, v99
	v_cvt_pk_bf16_f32 v105, v94, v95
	v_lshl_add_u64 v[108:109], v[142:143], 1, v[108:109]
	v_add_f32_e32 v92, v93, v96
	v_mul_f32_e32 v93, v95, v95
	global_store_dwordx4 v[108:109], v[102:105], off
	v_fmac_f32_e32 v93, v94, v94
	s_nop 0
	v_add_f32_e32 v102, v93, v92
	s_nop 0
	s_nop 0
	s_waitcnt vmcnt(4)
	v_pk_fma_f32 v[86:87], v[86:87], 0.5, v[218:219] op_sel_hi:[1,0,1]
	s_waitcnt vmcnt(3)
	v_pk_fma_f32 v[90:91], v[90:91], 0.5, v[222:223] op_sel_hi:[1,0,1]
	v_pk_fma_f32 v[88:89], v[88:89], 0.5, v[220:221] op_sel_hi:[1,0,1]
	v_pk_fma_f32 v[84:85], v[84:85], 0.5, v[216:217] op_sel_hi:[1,0,1]
	global_store_dwordx4 v[106:107], v[88:91], off offset:512
	global_store_dwordx4 v[106:107], v[84:87], off offset:528
	v_cvt_pk_bf16_f32 v92, v88, v89
	v_mul_f32_e32 v89, v89, v89
	v_fmac_f32_e32 v89, v88, v88
	v_mul_f32_e32 v88, v91, v91
	v_cvt_pk_bf16_f32 v94, v84, v85
	v_fmac_f32_e32 v88, v90, v90
	v_mul_f32_e32 v85, v85, v85
	v_add_f32_e32 v88, v89, v88
	v_fmac_f32_e32 v85, v84, v84
	v_add_f32_e32 v84, v85, v88
	v_mul_f32_e32 v85, v87, v87
	v_fmac_f32_e32 v85, v86, v86
	v_add_f32_e32 v84, v85, v84
	v_add_f32_e32 v84, v102, v84
	ds_bpermute_b32 v85, v195, v84
	v_cvt_pk_bf16_f32 v93, v90, v91
	v_cvt_pk_bf16_f32 v95, v86, v87
	global_store_dwordx4 v[108:109], v[92:95], off offset:256
	s_waitcnt lgkmcnt(0)
	v_add_f32_e32 v84, v84, v85
	ds_bpermute_b32 v85, v3, v84
	s_and_saveexec_b64 s[16:17], s[6:7]
	s_cbranch_execz .LBB0_330
	s_waitcnt lgkmcnt(0)
	v_add_f32_e32 v86, v84, v85
	v_lshl_add_u64 v[84:85], v[100:101], 2, s[84:85]
	v_mov_b32_e32 v232, v84
	v_mov_b32_e32 v233, v85
	v_mov_b32_e32 v234, v86
; __device__ __forceinline__ u32x4 pack8(f32x4 a, f32x4 b) { u32x4 w; w.x = pk2(a[0], a[1]); w.y = pk2(a[2], a[3]); w.z = pk2(b[0], b[1]); w.w = pk2(b[2], b[3]); return w; }
; __device__ __forceinline__ float dot8(f32x4 a, f32x4 b) { return (a[0] * a[0] + a[1] * a[1]) + (a[2] * a[2] + a[3] * a[3]) + (b[0] * b[0] + b[1] * b[1]) + (b[2] * b[2] + b[3] * b[3]); }
; __device__ __forceinline__ float red_fq(float s) { s += __shfl_xor(s, 16); s += __shfl_xor(s, 32); return s; }
;     __device__ __forceinline__ void operator()(AccRef acc, const Unit& u, int wr, int wc, int fr, int fq) const {
;     ...
;             const float* rp = (row < MP) ? res0 + (size_t)row * DM : res1 + (size_t)(row - MP) * DM;
;             float s = 0.f;
;             _Pragma("unroll") for (int bj = 0; bj < 2; ++bj) { const int col = col0 + bj * 128;
;                 f32x4 v0 = *(const f32x4*)(rp + col) + acc[ai][bj][m][0] * scale, v1 = *(const f32x4*)(rp + col + 4) + acc[ai][bj][m][1] * scale;
;                 *(f32x4*)(out + (size_t)row * DM + col) = v0; *(f32x4*)(out + (size_t)row * DM + col + 4) = v1;
;                 if (WB) *(u32x4*)(ob + (size_t)row * DM + col) = pack8(v0, v1);
;                 s += dot8(v0, v1); }
;             s = red_fq(s); if (fq == 0) unsafeAtomicAdd(ss + row, s);
.LBB0_330:
	s_or_b64 exec, exec, s[16:17]
	s_waitcnt lgkmcnt(0)
	v_or_b32_e32 v84, 48, v144
	v_cmp_lt_i32_e32 vcc, s91, v84
	s_and_saveexec_b64 s[16:17], vcc
	s_xor_b64 s[16:17], exec, s[16:17]
	v_add_u32_e32 v86, 0xffff8030, v144
	v_mov_b32_e32 v87, v2
	v_lshlrev_b64 v[86:87], 12, v[86:87]
	v_lshl_add_u64 v[86:87], s[38:39], 0, v[86:87]
	v_mov_b32_e32 v85, v2
	s_andn2_saveexec_b64 s[16:17], s[16:17]
	v_ashrrev_i32_e32 v85, 31, v84
	v_lshlrev_b64 v[86:87], 12, v[84:85]
	v_lshl_add_u64 v[86:87], s[36:37], 0, v[86:87]
	s_or_b64 exec, exec, s[16:17]
	v_lshl_add_u64 v[94:95], v[86:87], 0, v[146:147]
	global_load_dwordx4 v[86:89], v[94:95], off offset:16
	global_load_dwordx4 v[90:93], v[94:95], off
	global_load_dwordx4 v[216:219], v[94:95], off offset:528
	global_load_dwordx4 v[220:223], v[94:95], off offset:512
	s_waitcnt vmcnt(3)
	v_pk_fma_f32 v[76:77], v[76:77], 0.5, v[86:87] op_sel_hi:[1,0,1]
	v_lshlrev_b64 v[86:87], 12, v[84:85]
	v_lshl_add_u64 v[86:87], s[30:31], 0, v[86:87]
	s_waitcnt vmcnt(2)
	v_pk_fma_f32 v[82:83], v[82:83], 0.5, v[92:93] op_sel_hi:[1,0,1]
	v_pk_fma_f32 v[80:81], v[80:81], 0.5, v[90:91] op_sel_hi:[1,0,1]
	v_lshl_add_u64 v[90:91], v[86:87], 0, v[146:147]
	v_pk_fma_f32 v[78:79], v[78:79], 0.5, v[88:89] op_sel_hi:[1,0,1]
	global_store_dwordx4 v[90:91], v[80:83], off
	global_store_dwordx4 v[90:91], v[76:79], off offset:16
	v_cvt_pk_bf16_f32 v86, v80, v81
	v_mul_f32_e32 v81, v81, v81
	v_fmac_f32_e32 v81, v80, v80
	v_mul_f32_e32 v80, v83, v83
	v_cvt_pk_bf16_f32 v88, v76, v77
	v_lshlrev_b64 v[92:93], 11, v[84:85]
	v_fmac_f32_e32 v80, v82, v82
	v_mul_f32_e32 v77, v77, v77
	v_lshl_add_u64 v[92:93], s[18:19], 0, v[92:93]
	v_add_f32_e32 v80, v81, v80
	v_fmac_f32_e32 v77, v76, v76
	v_cvt_pk_bf16_f32 v87, v82, v83
	v_cvt_pk_bf16_f32 v89, v78, v79
	v_lshl_add_u64 v[92:93], v[142:143], 1, v[92:93]
	v_add_f32_e32 v76, v77, v80
	v_mul_f32_e32 v77, v79, v79
	global_store_dwordx4 v[92:93], v[86:89], off
	v_fmac_f32_e32 v77, v78, v78
	s_nop 0
	v_add_f32_e32 v86, v77, v76
	s_nop 0
	s_nop 0
	s_waitcnt vmcnt(4)
	v_pk_fma_f32 v[70:71], v[70:71], 0.5, v[218:219] op_sel_hi:[1,0,1]
	s_waitcnt vmcnt(3)
	v_pk_fma_f32 v[74:75], v[74:75], 0.5, v[222:223] op_sel_hi:[1,0,1]
	v_pk_fma_f32 v[72:73], v[72:73], 0.5, v[220:221] op_sel_hi:[1,0,1]
	v_pk_fma_f32 v[68:69], v[68:69], 0.5, v[216:217] op_sel_hi:[1,0,1]
	global_store_dwordx4 v[90:91], v[72:75], off offset:512
	global_store_dwordx4 v[90:91], v[68:71], off offset:528
	v_cvt_pk_bf16_f32 v76, v72, v73
	v_mul_f32_e32 v73, v73, v73
	v_fmac_f32_e32 v73, v72, v72
	v_mul_f32_e32 v72, v75, v75
	v_cvt_pk_bf16_f32 v78, v68, v69
	v_fmac_f32_e32 v72, v74, v74
	v_mul_f32_e32 v69, v69, v69
	v_add_f32_e32 v72, v73, v72
	v_fmac_f32_e32 v69, v68, v68
	v_add_f32_e32 v68, v69, v72
	v_mul_f32_e32 v69, v71, v71
	v_fmac_f32_e32 v69, v70, v70
	v_add_f32_e32 v68, v69, v68
	v_add_f32_e32 v68, v86, v68
	ds_bpermute_b32 v69, v195, v68
	v_cvt_pk_bf16_f32 v77, v74, v75
	v_cvt_pk_bf16_f32 v79, v70, v71
	global_store_dwordx4 v[92:93], v[76:79], off offset:256
	s_waitcnt lgkmcnt(0)
	v_add_f32_e32 v68, v68, v69
	ds_bpermute_b32 v69, v3, v68
	s_and_saveexec_b64 s[16:17], s[6:7]
	s_cbranch_execz .LBB0_336
	s_waitcnt lgkmcnt(0)
	v_add_f32_e32 v70, v68, v69
	v_lshl_add_u64 v[68:69], v[84:85], 2, s[84:85]
	v_mov_b32_e32 v236, v68
	v_mov_b32_e32 v237, v69
	v_mov_b32_e32 v238, v70
.LBB0_336:
	s_or_b64 exec, exec, s[16:17]
	s_movk_i32 s10, 0x7f7f
	s_waitcnt lgkmcnt(0)
	v_add_u32_e32 v68, 0x80, v144
	v_cmp_lt_i32_e32 vcc, s10, v144
	s_and_saveexec_b64 s[16:17], vcc
	s_xor_b64 s[16:17], exec, s[16:17]
	v_add_u32_e32 v70, 0xffff8080, v144
	v_mov_b32_e32 v71, v2
	v_lshlrev_b64 v[70:71], 12, v[70:71]
	v_lshl_add_u64 v[70:71], s[38:39], 0, v[70:71]
	v_mov_b32_e32 v69, v2
	s_andn2_saveexec_b64 s[16:17], s[16:17]
	v_ashrrev_i32_e32 v69, 31, v68
	v_lshlrev_b64 v[70:71], 12, v[68:69]
	v_lshl_add_u64 v[70:71], s[36:37], 0, v[70:71]
	s_or_b64 exec, exec, s[16:17]
	v_lshl_add_u64 v[78:79], v[70:71], 0, v[146:147]
	global_load_dwordx4 v[70:73], v[78:79], off offset:16
	global_load_dwordx4 v[74:77], v[78:79], off
	global_load_dwordx4 v[216:219], v[78:79], off offset:528
	global_load_dwordx4 v[220:223], v[78:79], off offset:512
	s_waitcnt vmcnt(3)
	v_pk_fma_f32 v[60:61], v[60:61], 0.5, v[70:71] op_sel_hi:[1,0,1]
	v_lshlrev_b64 v[70:71], 12, v[68:69]
	v_lshl_add_u64 v[70:71], s[30:31], 0, v[70:71]
	s_waitcnt vmcnt(2)
	v_pk_fma_f32 v[66:67], v[66:67], 0.5, v[76:77] op_sel_hi:[1,0,1]
	v_pk_fma_f32 v[64:65], v[64:65], 0.5, v[74:75] op_sel_hi:[1,0,1]
	v_lshl_add_u64 v[74:75], v[70:71], 0, v[146:147]
	v_pk_fma_f32 v[62:63], v[62:63], 0.5, v[72:73] op_sel_hi:[1,0,1]
	global_store_dwordx4 v[74:75], v[64:67], off
	global_store_dwordx4 v[74:75], v[60:63], off offset:16
	v_cvt_pk_bf16_f32 v70, v64, v65
	v_mul_f32_e32 v65, v65, v65
	v_fmac_f32_e32 v65, v64, v64
	v_mul_f32_e32 v64, v67, v67
	v_cvt_pk_bf16_f32 v72, v60, v61
	v_lshlrev_b64 v[76:77], 11, v[68:69]
	v_fmac_f32_e32 v64, v66, v66
	v_mul_f32_e32 v61, v61, v61
	v_lshl_add_u64 v[76:77], s[18:19], 0, v[76:77]
	v_add_f32_e32 v64, v65, v64
	v_fmac_f32_e32 v61, v60, v60
	v_cvt_pk_bf16_f32 v71, v66, v67
	v_cvt_pk_bf16_f32 v73, v62, v63
	v_lshl_add_u64 v[76:77], v[142:143], 1, v[76:77]
	v_add_f32_e32 v60, v61, v64
	v_mul_f32_e32 v61, v63, v63
	global_store_dwordx4 v[76:77], v[70:73], off
	v_fmac_f32_e32 v61, v62, v62
	s_nop 0
	v_add_f32_e32 v70, v61, v60
	s_nop 0
	s_nop 0
	s_waitcnt vmcnt(4)
	v_pk_fma_f32 v[54:55], v[54:55], 0.5, v[218:219] op_sel_hi:[1,0,1]
	s_waitcnt vmcnt(3)
	v_pk_fma_f32 v[58:59], v[58:59], 0.5, v[222:223] op_sel_hi:[1,0,1]
	v_pk_fma_f32 v[56:57], v[56:57], 0.5, v[220:221] op_sel_hi:[1,0,1]
	v_pk_fma_f32 v[52:53], v[52:53], 0.5, v[216:217] op_sel_hi:[1,0,1]
	global_store_dwordx4 v[74:75], v[56:59], off offset:512
	global_store_dwordx4 v[74:75], v[52:55], off offset:528
	v_cvt_pk_bf16_f32 v60, v56, v57
	v_mul_f32_e32 v57, v57, v57
	v_fmac_f32_e32 v57, v56, v56
	v_mul_f32_e32 v56, v59, v59
	v_cvt_pk_bf16_f32 v62, v52, v53
	v_fmac_f32_e32 v56, v58, v58
	v_mul_f32_e32 v53, v53, v53
	v_add_f32_e32 v56, v57, v56
	v_fmac_f32_e32 v53, v52, v52
	v_add_f32_e32 v52, v53, v56
	v_mul_f32_e32 v53, v55, v55
	v_fmac_f32_e32 v53, v54, v54
	v_add_f32_e32 v52, v53, v52
	v_add_f32_e32 v52, v70, v52
	ds_bpermute_b32 v53, v195, v52
	v_cvt_pk_bf16_f32 v61, v58, v59
	v_cvt_pk_bf16_f32 v63, v54, v55
	global_store_dwordx4 v[76:77], v[60:63], off offset:256
	s_waitcnt lgkmcnt(0)
	v_add_f32_e32 v52, v52, v53
	ds_bpermute_b32 v53, v3, v52
	s_and_saveexec_b64 s[16:17], s[6:7]
	s_cbranch_execz .LBB0_342
	s_waitcnt lgkmcnt(0)
	v_add_f32_e32 v54, v52, v53
	v_lshl_add_u64 v[52:53], v[68:69], 2, s[84:85]
	v_mov_b32_e32 v240, v52
	v_mov_b32_e32 v241, v53
	v_mov_b32_e32 v242, v54
; __device__ __forceinline__ u32x4 pack8(f32x4 a, f32x4 b) { u32x4 w; w.x = pk2(a[0], a[1]); w.y = pk2(a[2], a[3]); w.z = pk2(b[0], b[1]); w.w = pk2(b[2], b[3]); return w; }
; __device__ __forceinline__ float dot8(f32x4 a, f32x4 b) { return (a[0] * a[0] + a[1] * a[1]) + (a[2] * a[2] + a[3] * a[3]) + (b[0] * b[0] + b[1] * b[1]) + (b[2] * b[2] + b[3] * b[3]); }
; __device__ __forceinline__ float red_fq(float s) { s += __shfl_xor(s, 16); s += __shfl_xor(s, 32); return s; }
;     __device__ __forceinline__ void operator()(AccRef acc, const Unit& u, int wr, int wc, int fr, int fq) const {
;     ...
;             const float* rp = (row < MP) ? res0 + (size_t)row * DM : res1 + (size_t)(row - MP) * DM;
;             float s = 0.f;
;             _Pragma("unroll") for (int bj = 0; bj < 2; ++bj) { const int col = col0 + bj * 128;
;                 f32x4 v0 = *(const f32x4*)(rp + col) + acc[ai][bj][m][0] * scale, v1 = *(const f32x4*)(rp + col + 4) + acc[ai][bj][m][1] * scale;
;                 *(f32x4*)(out + (size_t)row * DM + col) = v0; *(f32x4*)(out + (size_t)row * DM + col + 4) = v1;
;                 if (WB) *(u32x4*)(ob + (size_t)row * DM + col) = pack8(v0, v1);
;                 s += dot8(v0, v1); }
;             s = red_fq(s); if (fq == 0) unsafeAtomicAdd(ss + row, s);
.LBB0_342:
	s_or_b64 exec, exec, s[16:17]
	s_movk_i32 s10, 0x7f6f
	s_waitcnt lgkmcnt(0)
	v_add_u32_e32 v52, 0x90, v144
	v_cmp_lt_i32_e32 vcc, s10, v144
	s_and_saveexec_b64 s[16:17], vcc
	s_xor_b64 s[16:17], exec, s[16:17]
	v_add_u32_e32 v54, 0xffff8090, v144
	v_mov_b32_e32 v55, v2
	v_lshlrev_b64 v[54:55], 12, v[54:55]
	v_lshl_add_u64 v[54:55], s[38:39], 0, v[54:55]
	v_mov_b32_e32 v53, v2
	s_andn2_saveexec_b64 s[16:17], s[16:17]
	v_ashrrev_i32_e32 v53, 31, v52
	v_lshlrev_b64 v[54:55], 12, v[52:53]
	v_lshl_add_u64 v[54:55], s[36:37], 0, v[54:55]
	s_or_b64 exec, exec, s[16:17]
	v_lshl_add_u64 v[62:63], v[54:55], 0, v[146:147]
	global_load_dwordx4 v[54:57], v[62:63], off offset:16
	global_load_dwordx4 v[58:61], v[62:63], off
	global_load_dwordx4 v[216:219], v[62:63], off offset:528
	global_load_dwordx4 v[220:223], v[62:63], off offset:512
	s_waitcnt vmcnt(3)
	v_pk_fma_f32 v[44:45], v[44:45], 0.5, v[54:55] op_sel_hi:[1,0,1]
	v_lshlrev_b64 v[54:55], 12, v[52:53]
	v_lshl_add_u64 v[54:55], s[30:31], 0, v[54:55]
	s_waitcnt vmcnt(2)
	v_pk_fma_f32 v[50:51], v[50:51], 0.5, v[60:61] op_sel_hi:[1,0,1]
	v_pk_fma_f32 v[48:49], v[48:49], 0.5, v[58:59] op_sel_hi:[1,0,1]
	v_lshl_add_u64 v[58:59], v[54:55], 0, v[146:147]
	v_pk_fma_f32 v[46:47], v[46:47], 0.5, v[56:57] op_sel_hi:[1,0,1]
	global_store_dwordx4 v[58:59], v[48:51], off
	global_store_dwordx4 v[58:59], v[44:47], off offset:16
	v_cvt_pk_bf16_f32 v54, v48, v49
	v_mul_f32_e32 v49, v49, v49
	v_fmac_f32_e32 v49, v48, v48
	v_mul_f32_e32 v48, v51, v51
	v_cvt_pk_bf16_f32 v56, v44, v45
	v_lshlrev_b64 v[60:61], 11, v[52:53]
	v_fmac_f32_e32 v48, v50, v50
	v_mul_f32_e32 v45, v45, v45
	v_lshl_add_u64 v[60:61], s[18:19], 0, v[60:61]
	v_add_f32_e32 v48, v49, v48
	v_fmac_f32_e32 v45, v44, v44
	v_cvt_pk_bf16_f32 v55, v50, v51
	v_cvt_pk_bf16_f32 v57, v46, v47
	v_lshl_add_u64 v[60:61], v[142:143], 1, v[60:61]
	v_add_f32_e32 v44, v45, v48
	v_mul_f32_e32 v45, v47, v47
	global_store_dwordx4 v[60:61], v[54:57], off
	v_fmac_f32_e32 v45, v46, v46
	s_nop 0
	v_add_f32_e32 v54, v45, v44
	s_nop 0
	s_nop 0
	s_waitcnt vmcnt(4)
	v_pk_fma_f32 v[38:39], v[38:39], 0.5, v[218:219] op_sel_hi:[1,0,1]
	s_waitcnt vmcnt(3)
	v_pk_fma_f32 v[42:43], v[42:43], 0.5, v[222:223] op_sel_hi:[1,0,1]
	v_pk_fma_f32 v[40:41], v[40:41], 0.5, v[220:221] op_sel_hi:[1,0,1]
	v_pk_fma_f32 v[36:37], v[36:37], 0.5, v[216:217] op_sel_hi:[1,0,1]
	global_store_dwordx4 v[58:59], v[40:43], off offset:512
	global_store_dwordx4 v[58:59], v[36:39], off offset:528
	v_cvt_pk_bf16_f32 v44, v40, v41
	v_mul_f32_e32 v41, v41, v41
	v_fmac_f32_e32 v41, v40, v40
	v_mul_f32_e32 v40, v43, v43
	v_cvt_pk_bf16_f32 v46, v36, v37
	v_fmac_f32_e32 v40, v42, v42
	v_mul_f32_e32 v37, v37, v37
	v_add_f32_e32 v40, v41, v40
	v_fmac_f32_e32 v37, v36, v36
	v_add_f32_e32 v36, v37, v40
	v_mul_f32_e32 v37, v39, v39
	v_fmac_f32_e32 v37, v38, v38
	v_add_f32_e32 v36, v37, v36
	v_add_f32_e32 v36, v54, v36
	ds_bpermute_b32 v37, v195, v36
	v_cvt_pk_bf16_f32 v45, v42, v43
	v_cvt_pk_bf16_f32 v47, v38, v39
	global_store_dwordx4 v[60:61], v[44:47], off offset:256
	s_waitcnt lgkmcnt(0)
	v_add_f32_e32 v36, v36, v37
	ds_bpermute_b32 v37, v3, v36
	s_and_saveexec_b64 s[16:17], s[6:7]
	s_cbranch_execz .LBB0_348
	s_waitcnt lgkmcnt(0)
	v_add_f32_e32 v38, v36, v37
	v_lshl_add_u64 v[36:37], v[52:53], 2, s[84:85]
	v_mov_b32_e32 v244, v36
	v_mov_b32_e32 v245, v37
	v_mov_b32_e32 v246, v38
.LBB0_348:
	s_or_b64 exec, exec, s[16:17]
	s_movk_i32 s10, 0x7f5f
	s_waitcnt lgkmcnt(0)
	v_add_u32_e32 v36, 0xa0, v144
	v_cmp_lt_i32_e32 vcc, s10, v144
	s_and_saveexec_b64 s[16:17], vcc
	s_xor_b64 s[16:17], exec, s[16:17]
	v_add_u32_e32 v38, 0xffff80a0, v144
	v_mov_b32_e32 v39, v2
	v_lshlrev_b64 v[38:39], 12, v[38:39]
	v_lshl_add_u64 v[38:39], s[38:39], 0, v[38:39]
	v_mov_b32_e32 v37, v2
	s_andn2_saveexec_b64 s[16:17], s[16:17]
	v_ashrrev_i32_e32 v37, 31, v36
	v_lshlrev_b64 v[38:39], 12, v[36:37]
	v_lshl_add_u64 v[38:39], s[36:37], 0, v[38:39]
	s_or_b64 exec, exec, s[16:17]
	v_lshl_add_u64 v[46:47], v[38:39], 0, v[146:147]
	global_load_dwordx4 v[38:41], v[46:47], off offset:16
	global_load_dwordx4 v[42:45], v[46:47], off
	global_load_dwordx4 v[216:219], v[46:47], off offset:528
	global_load_dwordx4 v[220:223], v[46:47], off offset:512
	s_waitcnt vmcnt(3)
	v_pk_fma_f32 v[28:29], v[28:29], 0.5, v[38:39] op_sel_hi:[1,0,1]
	v_lshlrev_b64 v[38:39], 12, v[36:37]
	v_lshl_add_u64 v[38:39], s[30:31], 0, v[38:39]
	s_waitcnt vmcnt(2)
	v_pk_fma_f32 v[34:35], v[34:35], 0.5, v[44:45] op_sel_hi:[1,0,1]
	v_pk_fma_f32 v[32:33], v[32:33], 0.5, v[42:43] op_sel_hi:[1,0,1]
	v_lshl_add_u64 v[42:43], v[38:39], 0, v[146:147]
	v_pk_fma_f32 v[30:31], v[30:31], 0.5, v[40:41] op_sel_hi:[1,0,1]
	global_store_dwordx4 v[42:43], v[32:35], off
	global_store_dwordx4 v[42:43], v[28:31], off offset:16
	v_cvt_pk_bf16_f32 v38, v32, v33
	v_mul_f32_e32 v33, v33, v33
	v_fmac_f32_e32 v33, v32, v32
	v_mul_f32_e32 v32, v35, v35
	v_cvt_pk_bf16_f32 v40, v28, v29
	v_lshlrev_b64 v[44:45], 11, v[36:37]
	v_fmac_f32_e32 v32, v34, v34
	v_mul_f32_e32 v29, v29, v29
	v_lshl_add_u64 v[44:45], s[18:19], 0, v[44:45]
	v_add_f32_e32 v32, v33, v32
	v_fmac_f32_e32 v29, v28, v28
	v_cvt_pk_bf16_f32 v39, v34, v35
	v_cvt_pk_bf16_f32 v41, v30, v31
	v_lshl_add_u64 v[44:45], v[142:143], 1, v[44:45]
	v_add_f32_e32 v28, v29, v32
	v_mul_f32_e32 v29, v31, v31
	global_store_dwordx4 v[44:45], v[38:41], off
	v_fmac_f32_e32 v29, v30, v30
	s_nop 0
	v_add_f32_e32 v38, v29, v28
	s_nop 0
	s_nop 0
	s_waitcnt vmcnt(4)
	v_pk_fma_f32 v[22:23], v[22:23], 0.5, v[218:219] op_sel_hi:[1,0,1]
	s_waitcnt vmcnt(3)
	v_pk_fma_f32 v[26:27], v[26:27], 0.5, v[222:223] op_sel_hi:[1,0,1]
	v_pk_fma_f32 v[24:25], v[24:25], 0.5, v[220:221] op_sel_hi:[1,0,1]
	v_pk_fma_f32 v[20:21], v[20:21], 0.5, v[216:217] op_sel_hi:[1,0,1]
	global_store_dwordx4 v[42:43], v[24:27], off offset:512
	global_store_dwordx4 v[42:43], v[20:23], off offset:528
	v_cvt_pk_bf16_f32 v28, v24, v25
	v_mul_f32_e32 v25, v25, v25
	v_fmac_f32_e32 v25, v24, v24
	v_mul_f32_e32 v24, v27, v27
	v_cvt_pk_bf16_f32 v30, v20, v21
	v_fmac_f32_e32 v24, v26, v26
	v_mul_f32_e32 v21, v21, v21
	v_add_f32_e32 v24, v25, v24
	v_fmac_f32_e32 v21, v20, v20
	v_add_f32_e32 v20, v21, v24
	v_mul_f32_e32 v21, v23, v23
	v_fmac_f32_e32 v21, v22, v22
	v_add_f32_e32 v20, v21, v20
	v_add_f32_e32 v20, v38, v20
	ds_bpermute_b32 v21, v195, v20
	v_cvt_pk_bf16_f32 v29, v26, v27
	v_cvt_pk_bf16_f32 v31, v22, v23
	global_store_dwordx4 v[44:45], v[28:31], off offset:256
	s_waitcnt lgkmcnt(0)
	v_add_f32_e32 v20, v20, v21
	ds_bpermute_b32 v21, v3, v20
	s_and_saveexec_b64 s[16:17], s[6:7]
	s_cbranch_execz .LBB0_354
	s_waitcnt lgkmcnt(0)
	v_add_f32_e32 v22, v20, v21
	v_lshl_add_u64 v[20:21], v[36:37], 2, s[84:85]
	v_mov_b32_e32 v248, v20
	v_mov_b32_e32 v249, v21
	v_mov_b32_e32 v250, v22
; __device__ __forceinline__ u32x4 pack8(f32x4 a, f32x4 b) { u32x4 w; w.x = pk2(a[0], a[1]); w.y = pk2(a[2], a[3]); w.z = pk2(b[0], b[1]); w.w = pk2(b[2], b[3]); return w; }
; __device__ __forceinline__ float dot8(f32x4 a, f32x4 b) { return (a[0] * a[0] + a[1] * a[1]) + (a[2] * a[2] + a[3] * a[3]) + (b[0] * b[0] + b[1] * b[1]) + (b[2] * b[2] + b[3] * b[3]); }
; __device__ __forceinline__ float red_fq(float s) { s += __shfl_xor(s, 16); s += __shfl_xor(s, 32); return s; }
;     __device__ __forceinline__ void operator()(AccRef acc, const Unit& u, int wr, int wc, int fr, int fq) const {
;     ...
;             const float* rp = (row < MP) ? res0 + (size_t)row * DM : res1 + (size_t)(row - MP) * DM;
;             float s = 0.f;
;             _Pragma("unroll") for (int bj = 0; bj < 2; ++bj) { const int col = col0 + bj * 128;
;                 f32x4 v0 = *(const f32x4*)(rp + col) + acc[ai][bj][m][0] * scale, v1 = *(const f32x4*)(rp + col + 4) + acc[ai][bj][m][1] * scale;
;                 *(f32x4*)(out + (size_t)row * DM + col) = v0; *(f32x4*)(out + (size_t)row * DM + col + 4) = v1;
;                 if (WB) *(u32x4*)(ob + (size_t)row * DM + col) = pack8(v0, v1);
;                 s += dot8(v0, v1); }
;             s = red_fq(s); if (fq == 0) unsafeAtomicAdd(ss + row, s);
.LBB0_354:
	s_or_b64 exec, exec, s[16:17]
	s_movk_i32 s10, 0x7f4f
	s_waitcnt lgkmcnt(0)
	v_add_u32_e32 v20, 0xb0, v144
	v_cmp_lt_i32_e32 vcc, s10, v144
	s_and_saveexec_b64 s[16:17], vcc
	s_xor_b64 s[16:17], exec, s[16:17]
	v_add_u32_e32 v22, 0xffff80b0, v144
	v_mov_b32_e32 v23, v2
	v_lshlrev_b64 v[22:23], 12, v[22:23]
	v_lshl_add_u64 v[22:23], s[38:39], 0, v[22:23]
	v_mov_b32_e32 v21, v2
	s_andn2_saveexec_b64 s[16:17], s[16:17]
	v_ashrrev_i32_e32 v21, 31, v20
	v_lshlrev_b64 v[22:23], 12, v[20:21]
	v_lshl_add_u64 v[22:23], s[36:37], 0, v[22:23]
	s_or_b64 exec, exec, s[16:17]
	v_lshl_add_u64 v[30:31], v[22:23], 0, v[146:147]
	global_load_dwordx4 v[22:25], v[30:31], off offset:16
	global_load_dwordx4 v[26:29], v[30:31], off
	global_load_dwordx4 v[216:219], v[30:31], off offset:528
	global_load_dwordx4 v[220:223], v[30:31], off offset:512
	s_waitcnt vmcnt(3)
	v_pk_fma_f32 v[12:13], v[12:13], 0.5, v[22:23] op_sel_hi:[1,0,1]
	v_lshlrev_b64 v[22:23], 12, v[20:21]
	v_lshl_add_u64 v[22:23], s[30:31], 0, v[22:23]
	s_waitcnt vmcnt(2)
	v_pk_fma_f32 v[18:19], v[18:19], 0.5, v[28:29] op_sel_hi:[1,0,1]
	v_pk_fma_f32 v[16:17], v[16:17], 0.5, v[26:27] op_sel_hi:[1,0,1]
	v_lshl_add_u64 v[26:27], v[22:23], 0, v[146:147]
	v_pk_fma_f32 v[14:15], v[14:15], 0.5, v[24:25] op_sel_hi:[1,0,1]
	global_store_dwordx4 v[26:27], v[16:19], off
	global_store_dwordx4 v[26:27], v[12:15], off offset:16
	v_cvt_pk_bf16_f32 v22, v16, v17
	v_mul_f32_e32 v17, v17, v17
	v_fmac_f32_e32 v17, v16, v16
	v_mul_f32_e32 v16, v19, v19
	v_cvt_pk_bf16_f32 v24, v12, v13
	v_lshlrev_b64 v[28:29], 11, v[20:21]
	v_fmac_f32_e32 v16, v18, v18
	v_mul_f32_e32 v13, v13, v13
	v_lshl_add_u64 v[28:29], s[18:19], 0, v[28:29]
	v_add_f32_e32 v16, v17, v16
	v_fmac_f32_e32 v13, v12, v12
	v_cvt_pk_bf16_f32 v23, v18, v19
	v_cvt_pk_bf16_f32 v25, v14, v15
	v_lshl_add_u64 v[28:29], v[142:143], 1, v[28:29]
	v_add_f32_e32 v12, v13, v16
	v_mul_f32_e32 v13, v15, v15
	global_store_dwordx4 v[28:29], v[22:25], off
	v_fmac_f32_e32 v13, v14, v14
	s_nop 0
	v_add_f32_e32 v22, v13, v12
	s_nop 0
	s_nop 0
	s_waitcnt vmcnt(4)
	v_pk_fma_f32 v[6:7], v[6:7], 0.5, v[218:219] op_sel_hi:[1,0,1]
	s_waitcnt vmcnt(3)
	v_pk_fma_f32 v[10:11], v[10:11], 0.5, v[222:223] op_sel_hi:[1,0,1]
	v_pk_fma_f32 v[8:9], v[8:9], 0.5, v[220:221] op_sel_hi:[1,0,1]
	v_pk_fma_f32 v[4:5], v[4:5], 0.5, v[216:217] op_sel_hi:[1,0,1]
	global_store_dwordx4 v[26:27], v[8:11], off offset:512
	global_store_dwordx4 v[26:27], v[4:7], off offset:528
	v_cvt_pk_bf16_f32 v12, v8, v9
	v_mul_f32_e32 v9, v9, v9
	v_fmac_f32_e32 v9, v8, v8
	v_mul_f32_e32 v8, v11, v11
	v_cvt_pk_bf16_f32 v14, v4, v5
	v_fmac_f32_e32 v8, v10, v10
	v_mul_f32_e32 v5, v5, v5
	v_add_f32_e32 v8, v9, v8
	v_fmac_f32_e32 v5, v4, v4
	v_add_f32_e32 v4, v5, v8
	v_mul_f32_e32 v5, v7, v7
	v_fmac_f32_e32 v5, v6, v6
	v_add_f32_e32 v4, v5, v4
	v_add_f32_e32 v4, v22, v4
	ds_bpermute_b32 v5, v195, v4
	v_cvt_pk_bf16_f32 v13, v10, v11
	v_cvt_pk_bf16_f32 v15, v6, v7
	global_store_dwordx4 v[28:29], v[12:15], off offset:256
	s_waitcnt lgkmcnt(0)
	v_add_f32_e32 v4, v4, v5
	ds_bpermute_b32 v3, v3, v4
	s_and_saveexec_b64 s[16:17], s[6:7]
	s_cbranch_execz .LBB0_360
	s_waitcnt lgkmcnt(0)
	v_add_f32_e32 v3, v4, v3
	v_lshl_add_u64 v[4:5], v[20:21], 2, s[84:85]
	global_atomic_add_f32 v[4:5], v3, off
	global_atomic_add_f32 v[224:225], v226, off
	global_atomic_add_f32 v[228:229], v230, off
	global_atomic_add_f32 v[232:233], v234, off
	global_atomic_add_f32 v[236:237], v238, off
	global_atomic_add_f32 v[240:241], v242, off
	global_atomic_add_f32 v[244:245], v246, off
	global_atomic_add_f32 v[248:249], v250, off

; template <class Epi>
; __device__ __forceinline__ void gemm_phase(LAS unsigned char* lds, const Gemm g, const StaticOrder& S, const Epi& E) {
;     ...
;                 for (int sl = 0; sl < S.NS; ++sl) { if (sl == myslice) continue;
;                     const __amdgpu_buffer_rsrc_t qrs = __builtin_amdgcn_make_buffer_rsrc((void*)(T + (size_t)sl * 65536), 0, 262144, 0x00020000);
; #pragma unroll
;                     for (int a = 0; a < 2; ++a)
; #pragma unroll
;                         for (int m = 0; m < 4; ++m)
; #pragma unroll
;                             for (int b = 0; b < 2; ++b)
; #pragma unroll
;                                 for (int n = 0; n < 2; ++n) acc[a][b][m][n] += __builtin_bit_cast(f32x4, __builtin_amdgcn_raw_buffer_load_b128(qrs, (int)(toff + (((a * 4 + m) * 2 + b) * 2 + n) * 8192), 0, 16)); }
.LBB0_1388:
	s_lshl_b32 s16, s16, 18
	s_add_u32 s20, s45, s16
	s_addc_u32 s16, s47, 0
	s_and_b32 s21, s16, 0xffff
	buffer_load_dwordx4 v[196:199], v141, s[20:23], 0 offen sc1
	buffer_load_dwordx4 v[200:203], v152, s[20:23], 0 offen sc1
	buffer_load_dwordx4 v[204:207], v156, s[20:23], 0 offen sc1
	buffer_load_dwordx4 v[208:211], v157, s[20:23], 0 offen sc1
	buffer_load_dwordx4 v[212:215], v160, s[20:23], 0 offen sc1
	buffer_load_dwordx4 v[216:219], v161, s[20:23], 0 offen sc1
	buffer_load_dwordx4 v[220:223], v162, s[20:23], 0 offen sc1
	buffer_load_dwordx4 v[224:227], v163, s[20:23], 0 offen sc1
	s_waitcnt vmcnt(7)
	v_pk_add_f32 v[130:131], v[130:131], v[198:199]
	v_pk_add_f32 v[128:129], v[128:129], v[196:197]
	buffer_load_dwordx4 v[196:199], v164, s[20:23], 0 offen sc1
	s_waitcnt vmcnt(7)
	v_pk_add_f32 v[126:127], v[126:127], v[202:203]
	v_pk_add_f32 v[124:125], v[124:125], v[200:201]
	buffer_load_dwordx4 v[200:203], v165, s[20:23], 0 offen sc1
	s_waitcnt vmcnt(7)
	v_pk_add_f32 v[122:123], v[122:123], v[206:207]
	v_pk_add_f32 v[120:121], v[120:121], v[204:205]
	buffer_load_dwordx4 v[204:207], v166, s[20:23], 0 offen sc1
	s_waitcnt vmcnt(7)
	v_pk_add_f32 v[118:119], v[118:119], v[210:211]
	v_pk_add_f32 v[116:117], v[116:117], v[208:209]
	buffer_load_dwordx4 v[208:211], v167, s[20:23], 0 offen sc1
	s_waitcnt vmcnt(7)
	v_pk_add_f32 v[114:115], v[114:115], v[214:215]
	v_pk_add_f32 v[112:113], v[112:113], v[212:213]
	buffer_load_dwordx4 v[212:215], v168, s[20:23], 0 offen sc1
	s_waitcnt vmcnt(7)
	v_pk_add_f32 v[110:111], v[110:111], v[218:219]
	v_pk_add_f32 v[108:109], v[108:109], v[216:217]
	buffer_load_dwordx4 v[216:219], v169, s[20:23], 0 offen sc1
	s_waitcnt vmcnt(7)
	v_pk_add_f32 v[106:107], v[106:107], v[222:223]
	v_pk_add_f32 v[104:105], v[104:105], v[220:221]
	buffer_load_dwordx4 v[220:223], v170, s[20:23], 0 offen sc1
	s_waitcnt vmcnt(7)
	v_pk_add_f32 v[102:103], v[102:103], v[226:227]
	v_pk_add_f32 v[100:101], v[100:101], v[224:225]
	buffer_load_dwordx4 v[224:227], v171, s[20:23], 0 offen sc1
	s_waitcnt vmcnt(7)
	v_pk_add_f32 v[98:99], v[98:99], v[198:199]
	v_pk_add_f32 v[96:97], v[96:97], v[196:197]
	buffer_load_dwordx4 v[196:199], v172, s[20:23], 0 offen sc1
	s_waitcnt vmcnt(7)
	v_pk_add_f32 v[94:95], v[94:95], v[202:203]
	v_pk_add_f32 v[92:93], v[92:93], v[200:201]
	buffer_load_dwordx4 v[200:203], v173, s[20:23], 0 offen sc1
	s_waitcnt vmcnt(7)
	v_pk_add_f32 v[90:91], v[90:91], v[206:207]
	v_pk_add_f32 v[88:89], v[88:89], v[204:205]
	buffer_load_dwordx4 v[204:207], v174, s[20:23], 0 offen sc1
	s_waitcnt vmcnt(7)
	v_pk_add_f32 v[86:87], v[86:87], v[210:211]
	v_pk_add_f32 v[84:85], v[84:85], v[208:209]
	buffer_load_dwordx4 v[208:211], v175, s[20:23], 0 offen sc1
	s_waitcnt vmcnt(7)
	v_pk_add_f32 v[82:83], v[82:83], v[214:215]
	v_pk_add_f32 v[80:81], v[80:81], v[212:213]
	buffer_load_dwordx4 v[212:215], v176, s[20:23], 0 offen sc1
	s_waitcnt vmcnt(7)
	v_pk_add_f32 v[78:79], v[78:79], v[218:219]
	v_pk_add_f32 v[76:77], v[76:77], v[216:217]
	buffer_load_dwordx4 v[216:219], v177, s[20:23], 0 offen sc1
	s_waitcnt vmcnt(7)
	v_pk_add_f32 v[74:75], v[74:75], v[222:223]
	v_pk_add_f32 v[72:73], v[72:73], v[220:221]
	buffer_load_dwordx4 v[220:223], v178, s[20:23], 0 offen sc1
	s_waitcnt vmcnt(7)
	v_pk_add_f32 v[70:71], v[70:71], v[226:227]
	v_pk_add_f32 v[68:69], v[68:69], v[224:225]
	buffer_load_dwordx4 v[224:227], v179, s[20:23], 0 offen sc1
	s_waitcnt vmcnt(7)
	v_pk_add_f32 v[66:67], v[66:67], v[198:199]
	v_pk_add_f32 v[64:65], v[64:65], v[196:197]
	buffer_load_dwordx4 v[196:199], v180, s[20:23], 0 offen sc1
	s_waitcnt vmcnt(7)
	v_pk_add_f32 v[62:63], v[62:63], v[202:203]
	v_pk_add_f32 v[60:61], v[60:61], v[200:201]
	buffer_load_dwordx4 v[200:203], v181, s[20:23], 0 offen sc1
	s_waitcnt vmcnt(7)
	v_pk_add_f32 v[58:59], v[58:59], v[206:207]
	v_pk_add_f32 v[56:57], v[56:57], v[204:205]
	buffer_load_dwordx4 v[204:207], v182, s[20:23], 0 offen sc1
	s_waitcnt vmcnt(7)
	v_pk_add_f32 v[54:55], v[54:55], v[210:211]
	v_pk_add_f32 v[52:53], v[52:53], v[208:209]
	buffer_load_dwordx4 v[208:211], v183, s[20:23], 0 offen sc1
	s_waitcnt vmcnt(7)
	v_pk_add_f32 v[50:51], v[50:51], v[214:215]
	v_pk_add_f32 v[48:49], v[48:49], v[212:213]
	buffer_load_dwordx4 v[212:215], v184, s[20:23], 0 offen sc1
	s_waitcnt vmcnt(7)
	v_pk_add_f32 v[46:47], v[46:47], v[218:219]
	v_pk_add_f32 v[44:45], v[44:45], v[216:217]
	buffer_load_dwordx4 v[216:219], v185, s[20:23], 0 offen sc1
	s_waitcnt vmcnt(7)
	v_pk_add_f32 v[42:43], v[42:43], v[222:223]
	v_pk_add_f32 v[40:41], v[40:41], v[220:221]
	buffer_load_dwordx4 v[220:223], v186, s[20:23], 0 offen sc1
	s_waitcnt vmcnt(7)
	v_pk_add_f32 v[38:39], v[38:39], v[226:227]
	v_pk_add_f32 v[36:37], v[36:37], v[224:225]
	buffer_load_dwordx4 v[224:227], v187, s[20:23], 0 offen sc1
	s_waitcnt vmcnt(7)
	v_pk_add_f32 v[34:35], v[34:35], v[198:199]
	v_pk_add_f32 v[32:33], v[32:33], v[196:197]
	s_waitcnt vmcnt(6)
	v_pk_add_f32 v[30:31], v[30:31], v[202:203]
	v_pk_add_f32 v[28:29], v[28:29], v[200:201]
	s_waitcnt vmcnt(5)
	v_pk_add_f32 v[26:27], v[26:27], v[206:207]
	v_pk_add_f32 v[24:25], v[24:25], v[204:205]
	s_waitcnt vmcnt(4)
	v_pk_add_f32 v[22:23], v[22:23], v[210:211]
	v_pk_add_f32 v[20:21], v[20:21], v[208:209]
	s_waitcnt vmcnt(3)
	v_pk_add_f32 v[18:19], v[18:19], v[214:215]
	v_pk_add_f32 v[16:17], v[16:17], v[212:213]
	s_waitcnt vmcnt(2)
	v_pk_add_f32 v[14:15], v[14:15], v[218:219]
	v_pk_add_f32 v[12:13], v[12:13], v[216:217]
	s_waitcnt vmcnt(1)
	v_pk_add_f32 v[10:11], v[10:11], v[222:223]
	v_pk_add_f32 v[8:9], v[8:9], v[220:221]
	s_waitcnt vmcnt(0)
	v_pk_add_f32 v[6:7], v[6:7], v[226:227]
	v_pk_add_f32 v[4:5], v[4:5], v[224:225]

; __device__ __forceinline__ u32x4 pack8(f32x4 a, f32x4 b) { u32x4 w; w.x = pk2(a[0], a[1]); w.y = pk2(a[2], a[3]); w.z = pk2(b[0], b[1]); w.w = pk2(b[2], b[3]); return w; }
; __device__ __forceinline__ float dot8(f32x4 a, f32x4 b) { return (a[0] * a[0] + a[1] * a[1]) + (a[2] * a[2] + a[3] * a[3]) + (b[0] * b[0] + b[1] * b[1]) + (b[2] * b[2] + b[3] * b[3]); }
; __device__ __forceinline__ float red_fq(float s) { s += __shfl_xor(s, 16); s += __shfl_xor(s, 32); return s; }
;     __device__ __forceinline__ void operator()(AccRef acc, const Unit& u, int wr, int wc, int fr, int fq) const {
;     ...
;             const float* rp = (row < MP) ? res0 + (size_t)row * DM : res1 + (size_t)(row - MP) * DM;
;             float s = 0.f;
;             _Pragma("unroll") for (int bj = 0; bj < 2; ++bj) { const int col = col0 + bj * 128;
;                 f32x4 v0 = *(const f32x4*)(rp + col) + acc[ai][bj][m][0] * scale, v1 = *(const f32x4*)(rp + col + 4) + acc[ai][bj][m][1] * scale;
;                 *(f32x4*)(out + (size_t)row * DM + col) = v0; *(f32x4*)(out + (size_t)row * DM + col + 4) = v1;
;                 if (WB) *(u32x4*)(ob + (size_t)row * DM + col) = pack8(v0, v1);
;                 s += dot8(v0, v1); }
;             s = red_fq(s); if (fq == 0) unsafeAtomicAdd(ss + row, s);
.LBB0_1395:
	v_lshl_add_u32 v146, s54, 8, v155
	v_cmp_lt_i32_e32 vcc, s79, v146
	s_and_saveexec_b64 s[16:17], vcc
	s_xor_b64 s[16:17], exec, s[16:17]
	v_add_u32_e32 v136, 0xffff8000, v146
	v_mov_b32_e32 v137, v2
	v_lshlrev_b64 v[136:137], 12, v[136:137]
	v_lshl_add_u64 v[148:149], s[10:11], 0, v[136:137]
	v_mov_b32_e32 v147, v2
	s_andn2_saveexec_b64 s[16:17], s[16:17]
	v_ashrrev_i32_e32 v147, 31, v146
	v_lshlrev_b64 v[136:137], 12, v[146:147]
	v_lshl_add_u64 v[148:149], s[30:31], 0, v[136:137]
	s_or_b64 exec, exec, s[16:17]
	v_lshl_or_b32 v142, s52, 8, v188
	v_ashrrev_i32_e32 v143, 31, v142
	v_lshlrev_b64 v[144:145], 2, v[142:143]
	v_lshl_add_u64 v[148:149], v[148:149], 0, v[144:145]
	global_load_dwordx4 v[136:139], v[148:149], off
	global_load_dwordx4 v[196:199], v[148:149], off offset:16
	global_load_dwordx4 v[216:219], v[148:149], off offset:512
	global_load_dwordx4 v[220:223], v[148:149], off offset:528
	v_lshlrev_b64 v[200:201], 12, v[146:147]
	v_lshlrev_b64 v[202:203], 11, v[146:147]
	v_lshl_add_u64 v[200:201], s[30:31], 0, v[200:201]
	v_lshl_add_u64 v[202:203], s[18:19], 0, v[202:203]
	v_lshl_add_u64 v[202:203], v[142:143], 1, v[202:203]
	v_lshl_add_u64 v[200:201], v[200:201], 0, v[144:145]
	v_xor_b32_e32 v3, 16, v193
	s_waitcnt vmcnt(3)
	v_pk_add_f32 v[130:131], v[138:139], v[130:131]
	v_pk_add_f32 v[128:129], v[136:137], v[128:129]
	s_waitcnt vmcnt(2)
	v_pk_add_f32 v[126:127], v[198:199], v[126:127]
	v_pk_add_f32 v[124:125], v[196:197], v[124:125]
	v_cvt_pk_bf16_f32 v136, v128, v129
	v_cvt_pk_bf16_f32 v137, v130, v131
	v_cvt_pk_bf16_f32 v138, v124, v125
	v_cvt_pk_bf16_f32 v139, v126, v127
	global_store_dwordx4 v[200:201], v[128:131], off
	global_store_dwordx4 v[200:201], v[124:127], off offset:16
	global_store_dwordx4 v[202:203], v[136:139], off
	s_nop 0
	s_nop 0
	s_nop 0
	v_mul_f32_e32 v129, v129, v129
	v_mul_f32_e32 v131, v131, v131
	v_mul_f32_e32 v125, v125, v125
	v_fmac_f32_e32 v129, v128, v128
	v_fmac_f32_e32 v131, v130, v130
	v_mul_f32_e32 v127, v127, v127
	v_fmac_f32_e32 v125, v124, v124
	v_add_f32_e32 v124, v129, v131
	v_fmac_f32_e32 v127, v126, v126
	v_add_f32_e32 v124, v125, v124
	v_add_f32_e32 v130, v127, v124
	v_and_b32_e32 v148, 64, v193
	v_add_u32_e32 v148, 64, v148
	v_cmp_lt_i32_e32 vcc, v3, v148
	v_xor_b32_e32 v149, 32, v193
	s_waitcnt vmcnt(4)
	v_pk_add_f32 v[124:125], v[218:219], v[122:123]
	v_pk_add_f32 v[122:123], v[216:217], v[120:121]
	s_waitcnt vmcnt(3)
	v_pk_add_f32 v[126:127], v[220:221], v[116:117]
	v_mul_f32_e32 v116, v123, v123
	v_mul_f32_e32 v117, v125, v125
	v_pk_add_f32 v[128:129], v[222:223], v[118:119]
	v_mul_f32_e32 v118, v127, v127
	v_fmac_f32_e32 v116, v122, v122
	v_fmac_f32_e32 v117, v124, v124
	v_mul_f32_e32 v119, v129, v129
	v_fmac_f32_e32 v118, v126, v126
	v_add_f32_e32 v116, v116, v117
	v_add_f32_e32 v116, v118, v116
	v_fmac_f32_e32 v119, v128, v128
	v_cndmask_b32_e32 v3, v193, v3, vcc
	v_add_f32_e32 v116, v119, v116
	v_lshlrev_b32_e32 v3, 2, v3
	v_add_f32_e32 v116, v130, v116
	ds_bpermute_b32 v117, v3, v116
	v_cmp_lt_i32_e32 vcc, v149, v148
	global_store_dwordx4 v[200:201], v[122:125], off offset:512
	global_store_dwordx4 v[200:201], v[126:129], off offset:528
	v_cndmask_b32_e32 v148, v193, v149, vcc
	v_lshlrev_b32_e32 v120, 2, v148
	s_waitcnt lgkmcnt(0)
	v_add_f32_e32 v116, v116, v117
	ds_bpermute_b32 v117, v120, v116
	v_cvt_pk_bf16_f32 v122, v122, v123
	v_cvt_pk_bf16_f32 v123, v124, v125
	v_cvt_pk_bf16_f32 v124, v126, v127
	v_cvt_pk_bf16_f32 v125, v128, v129
	global_store_dwordx4 v[202:203], v[122:125], off offset:256
	s_and_saveexec_b64 s[16:17], s[6:7]
	s_cbranch_execz .LBB0_1401
	s_waitcnt lgkmcnt(0)
	v_add_f32_e32 v118, v116, v117
	v_lshl_add_u64 v[116:117], v[146:147], 2, s[12:13]
	v_mov_b32_e32 v224, v116
	v_mov_b32_e32 v225, v117
	v_mov_b32_e32 v226, v118
.LBB0_1401:
	s_or_b64 exec, exec, s[16:17]
	s_waitcnt lgkmcnt(0)
	v_or_b32_e32 v116, 16, v146
	v_cmp_lt_i32_e32 vcc, s79, v116
	s_and_saveexec_b64 s[16:17], vcc
	s_xor_b64 s[16:17], exec, s[16:17]
	v_add_u32_e32 v118, 0xffff8010, v146
	v_mov_b32_e32 v119, v2
	v_lshlrev_b64 v[118:119], 12, v[118:119]
	v_lshl_add_u64 v[118:119], s[10:11], 0, v[118:119]
	v_mov_b32_e32 v117, v2
	s_andn2_saveexec_b64 s[16:17], s[16:17]
	v_ashrrev_i32_e32 v117, 31, v116
	v_lshlrev_b64 v[118:119], 12, v[116:117]
	v_lshl_add_u64 v[118:119], s[30:31], 0, v[118:119]
	s_or_b64 exec, exec, s[16:17]
	v_lshl_add_u64 v[118:119], v[118:119], 0, v[144:145]
	global_load_dwordx4 v[122:125], v[118:119], off
	global_load_dwordx4 v[126:129], v[118:119], off offset:16
	global_load_dwordx4 v[216:219], v[118:119], off offset:512
	global_load_dwordx4 v[220:223], v[118:119], off offset:528
	v_lshlrev_b64 v[130:131], 12, v[116:117]
	v_lshlrev_b64 v[136:137], 11, v[116:117]
	v_lshl_add_u64 v[130:131], s[30:31], 0, v[130:131]
	v_lshl_add_u64 v[136:137], s[18:19], 0, v[136:137]
	v_lshl_add_u64 v[130:131], v[130:131], 0, v[144:145]
	v_lshl_add_u64 v[136:137], v[142:143], 1, v[136:137]
	s_waitcnt vmcnt(3)
	v_pk_add_f32 v[114:115], v[124:125], v[114:115]
	v_pk_add_f32 v[112:113], v[122:123], v[112:113]
	s_waitcnt vmcnt(2)
	v_pk_add_f32 v[110:111], v[128:129], v[110:111]
	v_pk_add_f32 v[108:109], v[126:127], v[108:109]
	v_cvt_pk_bf16_f32 v122, v112, v113
	v_cvt_pk_bf16_f32 v123, v114, v115
	v_cvt_pk_bf16_f32 v124, v108, v109
	v_cvt_pk_bf16_f32 v125, v110, v111
	global_store_dwordx4 v[130:131], v[112:115], off
	global_store_dwordx4 v[130:131], v[108:111], off offset:16
	global_store_dwordx4 v[136:137], v[122:125], off
	s_nop 0
	s_nop 0
	s_nop 0
	v_mul_f32_e32 v113, v113, v113
	v_mul_f32_e32 v115, v115, v115
	v_mul_f32_e32 v109, v109, v109
	v_fmac_f32_e32 v113, v112, v112
	v_fmac_f32_e32 v115, v114, v114
	v_mul_f32_e32 v111, v111, v111
	v_fmac_f32_e32 v109, v108, v108
	v_add_f32_e32 v108, v113, v115
	v_fmac_f32_e32 v111, v110, v110
	v_add_f32_e32 v108, v109, v108
	v_add_f32_e32 v112, v111, v108
	s_waitcnt vmcnt(4)
	v_pk_add_f32 v[106:107], v[218:219], v[106:107]
	v_pk_add_f32 v[104:105], v[216:217], v[104:105]
	s_waitcnt vmcnt(3)
	v_pk_add_f32 v[108:109], v[220:221], v[100:101]
	v_mul_f32_e32 v100, v105, v105
	v_mul_f32_e32 v101, v107, v107
	v_pk_add_f32 v[110:111], v[222:223], v[102:103]
	v_mul_f32_e32 v102, v109, v109
	v_fmac_f32_e32 v100, v104, v104
	v_fmac_f32_e32 v101, v106, v106
	v_mul_f32_e32 v103, v111, v111
	v_fmac_f32_e32 v102, v108, v108
	v_add_f32_e32 v100, v100, v101
	v_add_f32_e32 v100, v102, v100
	v_fmac_f32_e32 v103, v110, v110
	v_add_f32_e32 v100, v103, v100
	v_add_f32_e32 v100, v112, v100
	ds_bpermute_b32 v101, v3, v100
	global_store_dwordx4 v[130:131], v[104:107], off offset:512
	global_store_dwordx4 v[130:131], v[108:111], off offset:528
	v_cvt_pk_bf16_f32 v102, v104, v105
	v_cvt_pk_bf16_f32 v103, v106, v107
	v_cvt_pk_bf16_f32 v104, v108, v109
	s_waitcnt lgkmcnt(0)
	v_add_f32_e32 v100, v100, v101
	ds_bpermute_b32 v101, v120, v100
	v_cvt_pk_bf16_f32 v105, v110, v111
	global_store_dwordx4 v[136:137], v[102:105], off offset:256
	s_and_saveexec_b64 s[16:17], s[6:7]
	s_cbranch_execz .LBB0_1407
; __device__ __forceinline__ u32x4 pack8(f32x4 a, f32x4 b) { u32x4 w; w.x = pk2(a[0], a[1]); w.y = pk2(a[2], a[3]); w.z = pk2(b[0], b[1]); w.w = pk2(b[2], b[3]); return w; }
; __device__ __forceinline__ float dot8(f32x4 a, f32x4 b) { return (a[0] * a[0] + a[1] * a[1]) + (a[2] * a[2] + a[3] * a[3]) + (b[0] * b[0] + b[1] * b[1]) + (b[2] * b[2] + b[3] * b[3]); }
; __device__ __forceinline__ float red_fq(float s) { s += __shfl_xor(s, 16); s += __shfl_xor(s, 32); return s; }
;     __device__ __forceinline__ void operator()(AccRef acc, const Unit& u, int wr, int wc, int fr, int fq) const {
;     ...
;             const float* rp = (row < MP) ? res0 + (size_t)row * DM : res1 + (size_t)(row - MP) * DM;
;             float s = 0.f;
;             _Pragma("unroll") for (int bj = 0; bj < 2; ++bj) { const int col = col0 + bj * 128;
;                 f32x4 v0 = *(const f32x4*)(rp + col) + acc[ai][bj][m][0] * scale, v1 = *(const f32x4*)(rp + col + 4) + acc[ai][bj][m][1] * scale;
;                 *(f32x4*)(out + (size_t)row * DM + col) = v0; *(f32x4*)(out + (size_t)row * DM + col + 4) = v1;
;                 if (WB) *(u32x4*)(ob + (size_t)row * DM + col) = pack8(v0, v1);
;                 s += dot8(v0, v1); }
;             s = red_fq(s); if (fq == 0) unsafeAtomicAdd(ss + row, s);
	s_waitcnt lgkmcnt(0)
	v_add_f32_e32 v102, v100, v101
	v_lshl_add_u64 v[100:101], v[116:117], 2, s[12:13]
	v_mov_b32_e32 v228, v100
	v_mov_b32_e32 v229, v101
	v_mov_b32_e32 v230, v102
.LBB0_1407:
	s_or_b64 exec, exec, s[16:17]
	s_waitcnt lgkmcnt(0)
	v_or_b32_e32 v100, 32, v146
	v_cmp_lt_i32_e32 vcc, s79, v100
	s_and_saveexec_b64 s[16:17], vcc
	s_xor_b64 s[16:17], exec, s[16:17]
	v_add_u32_e32 v102, 0xffff8020, v146
	v_mov_b32_e32 v103, v2
	v_lshlrev_b64 v[102:103], 12, v[102:103]
	v_lshl_add_u64 v[102:103], s[10:11], 0, v[102:103]
	v_mov_b32_e32 v101, v2
	s_andn2_saveexec_b64 s[16:17], s[16:17]
	v_ashrrev_i32_e32 v101, 31, v100
	v_lshlrev_b64 v[102:103], 12, v[100:101]
	v_lshl_add_u64 v[102:103], s[30:31], 0, v[102:103]
	s_or_b64 exec, exec, s[16:17]
	v_lshl_add_u64 v[110:111], v[102:103], 0, v[144:145]
	global_load_dwordx4 v[102:105], v[110:111], off
	global_load_dwordx4 v[106:109], v[110:111], off offset:16
	global_load_dwordx4 v[216:219], v[110:111], off offset:512
	global_load_dwordx4 v[220:223], v[110:111], off offset:528
	v_lshlrev_b64 v[112:113], 12, v[100:101]
	v_lshlrev_b64 v[114:115], 11, v[100:101]
	v_lshl_add_u64 v[112:113], s[30:31], 0, v[112:113]
	v_lshl_add_u64 v[114:115], s[18:19], 0, v[114:115]
	v_lshl_add_u64 v[112:113], v[112:113], 0, v[144:145]
	v_lshl_add_u64 v[114:115], v[142:143], 1, v[114:115]
	s_waitcnt vmcnt(3)
	v_pk_add_f32 v[98:99], v[104:105], v[98:99]
	v_pk_add_f32 v[96:97], v[102:103], v[96:97]
	s_waitcnt vmcnt(2)
	v_pk_add_f32 v[94:95], v[108:109], v[94:95]
	v_pk_add_f32 v[92:93], v[106:107], v[92:93]
	v_cvt_pk_bf16_f32 v102, v96, v97
	v_cvt_pk_bf16_f32 v103, v98, v99
	v_cvt_pk_bf16_f32 v104, v92, v93
	v_cvt_pk_bf16_f32 v105, v94, v95
	global_store_dwordx4 v[112:113], v[96:99], off
	global_store_dwordx4 v[112:113], v[92:95], off offset:16
	global_store_dwordx4 v[114:115], v[102:105], off
	s_nop 0
	s_nop 0
	s_nop 0
	v_mul_f32_e32 v97, v97, v97
	v_mul_f32_e32 v99, v99, v99
	v_mul_f32_e32 v93, v93, v93
	v_fmac_f32_e32 v97, v96, v96
	v_fmac_f32_e32 v99, v98, v98
	v_mul_f32_e32 v95, v95, v95
	v_fmac_f32_e32 v93, v92, v92
	v_add_f32_e32 v92, v97, v99
	v_fmac_f32_e32 v95, v94, v94
	v_add_f32_e32 v92, v93, v92
	v_add_f32_e32 v96, v95, v92
	s_waitcnt vmcnt(4)
	v_pk_add_f32 v[90:91], v[218:219], v[90:91]
	v_pk_add_f32 v[88:89], v[216:217], v[88:89]
	s_waitcnt vmcnt(3)
	v_pk_add_f32 v[92:93], v[220:221], v[84:85]
	v_mul_f32_e32 v84, v89, v89
	v_mul_f32_e32 v85, v91, v91
	v_pk_add_f32 v[94:95], v[222:223], v[86:87]
	v_mul_f32_e32 v86, v93, v93
	v_fmac_f32_e32 v84, v88, v88
	v_fmac_f32_e32 v85, v90, v90
	v_mul_f32_e32 v87, v95, v95
	v_fmac_f32_e32 v86, v92, v92
	v_add_f32_e32 v84, v84, v85
	v_add_f32_e32 v84, v86, v84
	v_fmac_f32_e32 v87, v94, v94
	v_add_f32_e32 v84, v87, v84
	v_add_f32_e32 v84, v96, v84
	ds_bpermute_b32 v85, v3, v84
	global_store_dwordx4 v[112:113], v[88:91], off offset:512
	global_store_dwordx4 v[112:113], v[92:95], off offset:528
	v_cvt_pk_bf16_f32 v86, v88, v89
	v_cvt_pk_bf16_f32 v87, v90, v91
	v_cvt_pk_bf16_f32 v88, v92, v93
	s_waitcnt lgkmcnt(0)
	v_add_f32_e32 v84, v84, v85
	ds_bpermute_b32 v85, v120, v84
	v_cvt_pk_bf16_f32 v89, v94, v95
	global_store_dwordx4 v[114:115], v[86:89], off offset:256
	s_and_saveexec_b64 s[16:17], s[6:7]
	s_cbranch_execz .LBB0_1413
	s_waitcnt lgkmcnt(0)
	v_add_f32_e32 v86, v84, v85
	v_lshl_add_u64 v[84:85], v[100:101], 2, s[12:13]
	v_mov_b32_e32 v232, v84
	v_mov_b32_e32 v233, v85
	v_mov_b32_e32 v234, v86
.LBB0_1413:
	s_or_b64 exec, exec, s[16:17]
	s_waitcnt lgkmcnt(0)
	v_or_b32_e32 v84, 48, v146
	v_cmp_lt_i32_e32 vcc, s79, v84
	s_and_saveexec_b64 s[16:17], vcc
	s_xor_b64 s[16:17], exec, s[16:17]
	v_add_u32_e32 v86, 0xffff8030, v146
	v_mov_b32_e32 v87, v2
	v_lshlrev_b64 v[86:87], 12, v[86:87]
	v_lshl_add_u64 v[86:87], s[10:11], 0, v[86:87]
	v_mov_b32_e32 v85, v2
	s_andn2_saveexec_b64 s[16:17], s[16:17]
	v_ashrrev_i32_e32 v85, 31, v84
	v_lshlrev_b64 v[86:87], 12, v[84:85]
	v_lshl_add_u64 v[86:87], s[30:31], 0, v[86:87]
	s_or_b64 exec, exec, s[16:17]
	v_lshl_add_u64 v[94:95], v[86:87], 0, v[144:145]
	global_load_dwordx4 v[86:89], v[94:95], off
	global_load_dwordx4 v[90:93], v[94:95], off offset:16
	global_load_dwordx4 v[216:219], v[94:95], off offset:512
	global_load_dwordx4 v[220:223], v[94:95], off offset:528
	v_lshlrev_b64 v[96:97], 12, v[84:85]
	v_lshlrev_b64 v[98:99], 11, v[84:85]
	v_lshl_add_u64 v[96:97], s[30:31], 0, v[96:97]
	v_lshl_add_u64 v[98:99], s[18:19], 0, v[98:99]
	v_lshl_add_u64 v[96:97], v[96:97], 0, v[144:145]
	v_lshl_add_u64 v[98:99], v[142:143], 1, v[98:99]
	s_waitcnt vmcnt(3)
	v_pk_add_f32 v[82:83], v[88:89], v[82:83]
	v_pk_add_f32 v[80:81], v[86:87], v[80:81]
	s_waitcnt vmcnt(2)
	v_pk_add_f32 v[78:79], v[92:93], v[78:79]
	v_pk_add_f32 v[76:77], v[90:91], v[76:77]
	v_cvt_pk_bf16_f32 v86, v80, v81
	v_cvt_pk_bf16_f32 v87, v82, v83
	v_cvt_pk_bf16_f32 v88, v76, v77
	v_cvt_pk_bf16_f32 v89, v78, v79
	global_store_dwordx4 v[96:97], v[80:83], off
	global_store_dwordx4 v[96:97], v[76:79], off offset:16
	global_store_dwordx4 v[98:99], v[86:89], off
	s_nop 0
	s_nop 0
	s_nop 0
	v_mul_f32_e32 v81, v81, v81
	v_mul_f32_e32 v83, v83, v83
	v_mul_f32_e32 v77, v77, v77
	v_fmac_f32_e32 v81, v80, v80
	v_fmac_f32_e32 v83, v82, v82
	v_mul_f32_e32 v79, v79, v79
	v_fmac_f32_e32 v77, v76, v76
	v_add_f32_e32 v76, v81, v83
	v_fmac_f32_e32 v79, v78, v78
	v_add_f32_e32 v76, v77, v76
	v_add_f32_e32 v80, v79, v76
	s_waitcnt vmcnt(4)
	v_pk_add_f32 v[74:75], v[218:219], v[74:75]
	v_pk_add_f32 v[72:73], v[216:217], v[72:73]
	s_waitcnt vmcnt(3)
	v_pk_add_f32 v[76:77], v[220:221], v[68:69]
	v_mul_f32_e32 v68, v73, v73
	v_mul_f32_e32 v69, v75, v75
	v_pk_add_f32 v[78:79], v[222:223], v[70:71]
	v_mul_f32_e32 v70, v77, v77
	v_fmac_f32_e32 v68, v72, v72
	v_fmac_f32_e32 v69, v74, v74
	v_mul_f32_e32 v71, v79, v79
	v_fmac_f32_e32 v70, v76, v76
	v_add_f32_e32 v68, v68, v69
	v_add_f32_e32 v68, v70, v68
	v_fmac_f32_e32 v71, v78, v78
	v_add_f32_e32 v68, v71, v68
	v_add_f32_e32 v68, v80, v68
	ds_bpermute_b32 v69, v3, v68
	global_store_dwordx4 v[96:97], v[72:75], off offset:512
	global_store_dwordx4 v[96:97], v[76:79], off offset:528
	v_cvt_pk_bf16_f32 v70, v72, v73
	v_cvt_pk_bf16_f32 v71, v74, v75
	v_cvt_pk_bf16_f32 v72, v76, v77
	s_waitcnt lgkmcnt(0)
	v_add_f32_e32 v68, v68, v69
	ds_bpermute_b32 v69, v120, v68
	v_cvt_pk_bf16_f32 v73, v78, v79
	global_store_dwordx4 v[98:99], v[70:73], off offset:256
	s_and_saveexec_b64 s[16:17], s[6:7]
	s_cbranch_execz .LBB0_1419
	s_waitcnt lgkmcnt(0)
	v_add_f32_e32 v70, v68, v69
	v_lshl_add_u64 v[68:69], v[84:85], 2, s[12:13]
	v_mov_b32_e32 v236, v68
	v_mov_b32_e32 v237, v69
	v_mov_b32_e32 v238, v70
; __device__ __forceinline__ u32x4 pack8(f32x4 a, f32x4 b) { u32x4 w; w.x = pk2(a[0], a[1]); w.y = pk2(a[2], a[3]); w.z = pk2(b[0], b[1]); w.w = pk2(b[2], b[3]); return w; }
; __device__ __forceinline__ float dot8(f32x4 a, f32x4 b) { return (a[0] * a[0] + a[1] * a[1]) + (a[2] * a[2] + a[3] * a[3]) + (b[0] * b[0] + b[1] * b[1]) + (b[2] * b[2] + b[3] * b[3]); }
; __device__ __forceinline__ float red_fq(float s) { s += __shfl_xor(s, 16); s += __shfl_xor(s, 32); return s; }
;     __device__ __forceinline__ void operator()(AccRef acc, const Unit& u, int wr, int wc, int fr, int fq) const {
;     ...
;             const float* rp = (row < MP) ? res0 + (size_t)row * DM : res1 + (size_t)(row - MP) * DM;
;             float s = 0.f;
;             _Pragma("unroll") for (int bj = 0; bj < 2; ++bj) { const int col = col0 + bj * 128;
;                 f32x4 v0 = *(const f32x4*)(rp + col) + acc[ai][bj][m][0] * scale, v1 = *(const f32x4*)(rp + col + 4) + acc[ai][bj][m][1] * scale;
;                 *(f32x4*)(out + (size_t)row * DM + col) = v0; *(f32x4*)(out + (size_t)row * DM + col + 4) = v1;
;                 if (WB) *(u32x4*)(ob + (size_t)row * DM + col) = pack8(v0, v1);
;                 s += dot8(v0, v1); }
;             s = red_fq(s); if (fq == 0) unsafeAtomicAdd(ss + row, s);
.LBB0_1419:
	s_or_b64 exec, exec, s[16:17]
	s_movk_i32 s16, 0x7f7f
	s_waitcnt lgkmcnt(0)
	v_add_u32_e32 v68, 0x80, v146
	v_cmp_lt_i32_e32 vcc, s16, v146
	s_and_saveexec_b64 s[16:17], vcc
	s_xor_b64 s[16:17], exec, s[16:17]
	v_add_u32_e32 v70, 0xffff8080, v146
	v_mov_b32_e32 v71, v2
	v_lshlrev_b64 v[70:71], 12, v[70:71]
	v_lshl_add_u64 v[70:71], s[10:11], 0, v[70:71]
	v_mov_b32_e32 v69, v2
	s_andn2_saveexec_b64 s[16:17], s[16:17]
	v_ashrrev_i32_e32 v69, 31, v68
	v_lshlrev_b64 v[70:71], 12, v[68:69]
	v_lshl_add_u64 v[70:71], s[30:31], 0, v[70:71]
	s_or_b64 exec, exec, s[16:17]
	v_lshl_add_u64 v[78:79], v[70:71], 0, v[144:145]
	global_load_dwordx4 v[70:73], v[78:79], off
	global_load_dwordx4 v[74:77], v[78:79], off offset:16
	global_load_dwordx4 v[216:219], v[78:79], off offset:512
	global_load_dwordx4 v[220:223], v[78:79], off offset:528
	v_lshlrev_b64 v[80:81], 12, v[68:69]
	v_lshlrev_b64 v[82:83], 11, v[68:69]
	v_lshl_add_u64 v[80:81], s[30:31], 0, v[80:81]
	v_lshl_add_u64 v[82:83], s[18:19], 0, v[82:83]
	v_lshl_add_u64 v[80:81], v[80:81], 0, v[144:145]
	v_lshl_add_u64 v[82:83], v[142:143], 1, v[82:83]
	s_waitcnt vmcnt(3)
	v_pk_add_f32 v[66:67], v[72:73], v[66:67]
	v_pk_add_f32 v[64:65], v[70:71], v[64:65]
	s_waitcnt vmcnt(2)
	v_pk_add_f32 v[62:63], v[76:77], v[62:63]
	v_pk_add_f32 v[60:61], v[74:75], v[60:61]
	v_cvt_pk_bf16_f32 v70, v64, v65
	v_cvt_pk_bf16_f32 v71, v66, v67
	v_cvt_pk_bf16_f32 v72, v60, v61
	v_cvt_pk_bf16_f32 v73, v62, v63
	global_store_dwordx4 v[80:81], v[64:67], off
	global_store_dwordx4 v[80:81], v[60:63], off offset:16
	global_store_dwordx4 v[82:83], v[70:73], off
	s_nop 0
	s_nop 0
	s_nop 0
	v_mul_f32_e32 v65, v65, v65
	v_mul_f32_e32 v67, v67, v67
	v_mul_f32_e32 v61, v61, v61
	v_fmac_f32_e32 v65, v64, v64
	v_fmac_f32_e32 v67, v66, v66
	v_mul_f32_e32 v63, v63, v63
	v_fmac_f32_e32 v61, v60, v60
	v_add_f32_e32 v60, v65, v67
	v_fmac_f32_e32 v63, v62, v62
	v_add_f32_e32 v60, v61, v60
	v_add_f32_e32 v64, v63, v60
	s_waitcnt vmcnt(4)
	v_pk_add_f32 v[58:59], v[218:219], v[58:59]
	v_pk_add_f32 v[56:57], v[216:217], v[56:57]
	s_waitcnt vmcnt(3)
	v_pk_add_f32 v[60:61], v[220:221], v[52:53]
	v_mul_f32_e32 v52, v57, v57
	v_mul_f32_e32 v53, v59, v59
	v_pk_add_f32 v[62:63], v[222:223], v[54:55]
	v_mul_f32_e32 v54, v61, v61
	v_fmac_f32_e32 v52, v56, v56
	v_fmac_f32_e32 v53, v58, v58
	v_mul_f32_e32 v55, v63, v63
	v_fmac_f32_e32 v54, v60, v60
	v_add_f32_e32 v52, v52, v53
	v_add_f32_e32 v52, v54, v52
	v_fmac_f32_e32 v55, v62, v62
	v_add_f32_e32 v52, v55, v52
	v_add_f32_e32 v52, v64, v52
	ds_bpermute_b32 v53, v3, v52
	global_store_dwordx4 v[80:81], v[56:59], off offset:512
	global_store_dwordx4 v[80:81], v[60:63], off offset:528
	v_cvt_pk_bf16_f32 v54, v56, v57
	v_cvt_pk_bf16_f32 v55, v58, v59
	v_cvt_pk_bf16_f32 v56, v60, v61
	s_waitcnt lgkmcnt(0)
	v_add_f32_e32 v52, v52, v53
	ds_bpermute_b32 v53, v120, v52
	v_cvt_pk_bf16_f32 v57, v62, v63
	global_store_dwordx4 v[82:83], v[54:57], off offset:256
	s_and_saveexec_b64 s[16:17], s[6:7]
	s_cbranch_execz .LBB0_1425
	s_waitcnt lgkmcnt(0)
	v_add_f32_e32 v54, v52, v53
	v_lshl_add_u64 v[52:53], v[68:69], 2, s[12:13]
	v_mov_b32_e32 v240, v52
	v_mov_b32_e32 v241, v53
	v_mov_b32_e32 v242, v54
.LBB0_1425:
	s_or_b64 exec, exec, s[16:17]
	s_movk_i32 s16, 0x7f6f
	s_waitcnt lgkmcnt(0)
	v_add_u32_e32 v52, 0x90, v146
	v_cmp_lt_i32_e32 vcc, s16, v146
	s_and_saveexec_b64 s[16:17], vcc
	s_xor_b64 s[16:17], exec, s[16:17]
	v_add_u32_e32 v54, 0xffff8090, v146
	v_mov_b32_e32 v55, v2
	v_lshlrev_b64 v[54:55], 12, v[54:55]
	v_lshl_add_u64 v[54:55], s[10:11], 0, v[54:55]
	v_mov_b32_e32 v53, v2
	s_andn2_saveexec_b64 s[16:17], s[16:17]
	v_ashrrev_i32_e32 v53, 31, v52
	v_lshlrev_b64 v[54:55], 12, v[52:53]
	v_lshl_add_u64 v[54:55], s[30:31], 0, v[54:55]
	s_or_b64 exec, exec, s[16:17]
	v_lshl_add_u64 v[62:63], v[54:55], 0, v[144:145]
	global_load_dwordx4 v[54:57], v[62:63], off
	global_load_dwordx4 v[58:61], v[62:63], off offset:16
	global_load_dwordx4 v[216:219], v[62:63], off offset:512
	global_load_dwordx4 v[220:223], v[62:63], off offset:528
	v_lshlrev_b64 v[64:65], 12, v[52:53]
	v_lshlrev_b64 v[66:67], 11, v[52:53]
	v_lshl_add_u64 v[64:65], s[30:31], 0, v[64:65]
	v_lshl_add_u64 v[66:67], s[18:19], 0, v[66:67]
	v_lshl_add_u64 v[64:65], v[64:65], 0, v[144:145]
	v_lshl_add_u64 v[66:67], v[142:143], 1, v[66:67]
	s_waitcnt vmcnt(3)
	v_pk_add_f32 v[50:51], v[56:57], v[50:51]
	v_pk_add_f32 v[48:49], v[54:55], v[48:49]
	s_waitcnt vmcnt(2)
	v_pk_add_f32 v[46:47], v[60:61], v[46:47]
	v_pk_add_f32 v[44:45], v[58:59], v[44:45]
	v_cvt_pk_bf16_f32 v54, v48, v49
	v_cvt_pk_bf16_f32 v55, v50, v51
	v_cvt_pk_bf16_f32 v56, v44, v45
	v_cvt_pk_bf16_f32 v57, v46, v47
	global_store_dwordx4 v[64:65], v[48:51], off
	global_store_dwordx4 v[64:65], v[44:47], off offset:16
	global_store_dwordx4 v[66:67], v[54:57], off
	s_nop 0
	s_nop 0
	s_nop 0
	v_mul_f32_e32 v49, v49, v49
	v_mul_f32_e32 v51, v51, v51
	v_mul_f32_e32 v45, v45, v45
	v_fmac_f32_e32 v49, v48, v48
	v_fmac_f32_e32 v51, v50, v50
	v_mul_f32_e32 v47, v47, v47
	v_fmac_f32_e32 v45, v44, v44
	v_add_f32_e32 v44, v49, v51
	v_fmac_f32_e32 v47, v46, v46
	v_add_f32_e32 v44, v45, v44
	v_add_f32_e32 v48, v47, v44
	s_waitcnt vmcnt(4)
	v_pk_add_f32 v[42:43], v[218:219], v[42:43]
	v_pk_add_f32 v[40:41], v[216:217], v[40:41]
	s_waitcnt vmcnt(3)
	v_pk_add_f32 v[44:45], v[220:221], v[36:37]
	v_mul_f32_e32 v36, v41, v41
	v_mul_f32_e32 v37, v43, v43
	v_pk_add_f32 v[46:47], v[222:223], v[38:39]
	v_mul_f32_e32 v38, v45, v45
	v_fmac_f32_e32 v36, v40, v40
	v_fmac_f32_e32 v37, v42, v42
	v_mul_f32_e32 v39, v47, v47
	v_fmac_f32_e32 v38, v44, v44
	v_add_f32_e32 v36, v36, v37
	v_add_f32_e32 v36, v38, v36
	v_fmac_f32_e32 v39, v46, v46
	v_add_f32_e32 v36, v39, v36
	v_add_f32_e32 v36, v48, v36
	ds_bpermute_b32 v37, v3, v36
	global_store_dwordx4 v[64:65], v[40:43], off offset:512
	global_store_dwordx4 v[64:65], v[44:47], off offset:528
	v_cvt_pk_bf16_f32 v38, v40, v41
	v_cvt_pk_bf16_f32 v39, v42, v43
	v_cvt_pk_bf16_f32 v40, v44, v45
	s_waitcnt lgkmcnt(0)
	v_add_f32_e32 v36, v36, v37
	ds_bpermute_b32 v37, v120, v36
	v_cvt_pk_bf16_f32 v41, v46, v47
	global_store_dwordx4 v[66:67], v[38:41], off offset:256
	s_and_saveexec_b64 s[16:17], s[6:7]
	s_cbranch_execz .LBB0_1431
	s_waitcnt lgkmcnt(0)
	v_add_f32_e32 v38, v36, v37
	v_lshl_add_u64 v[36:37], v[52:53], 2, s[12:13]
	v_mov_b32_e32 v244, v36
	v_mov_b32_e32 v245, v37
	v_mov_b32_e32 v246, v38
; __device__ __forceinline__ u32x4 pack8(f32x4 a, f32x4 b) { u32x4 w; w.x = pk2(a[0], a[1]); w.y = pk2(a[2], a[3]); w.z = pk2(b[0], b[1]); w.w = pk2(b[2], b[3]); return w; }
; __device__ __forceinline__ float dot8(f32x4 a, f32x4 b) { return (a[0] * a[0] + a[1] * a[1]) + (a[2] * a[2] + a[3] * a[3]) + (b[0] * b[0] + b[1] * b[1]) + (b[2] * b[2] + b[3] * b[3]); }
; __device__ __forceinline__ float red_fq(float s) { s += __shfl_xor(s, 16); s += __shfl_xor(s, 32); return s; }
;     __device__ __forceinline__ void operator()(AccRef acc, const Unit& u, int wr, int wc, int fr, int fq) const {
;     ...
;             const float* rp = (row < MP) ? res0 + (size_t)row * DM : res1 + (size_t)(row - MP) * DM;
;             float s = 0.f;
;             _Pragma("unroll") for (int bj = 0; bj < 2; ++bj) { const int col = col0 + bj * 128;
;                 f32x4 v0 = *(const f32x4*)(rp + col) + acc[ai][bj][m][0] * scale, v1 = *(const f32x4*)(rp + col + 4) + acc[ai][bj][m][1] * scale;
;                 *(f32x4*)(out + (size_t)row * DM + col) = v0; *(f32x4*)(out + (size_t)row * DM + col + 4) = v1;
;                 if (WB) *(u32x4*)(ob + (size_t)row * DM + col) = pack8(v0, v1);
;                 s += dot8(v0, v1); }
;             s = red_fq(s); if (fq == 0) unsafeAtomicAdd(ss + row, s);
.LBB0_1431:
	s_or_b64 exec, exec, s[16:17]
	s_movk_i32 s16, 0x7f5f
	s_waitcnt lgkmcnt(0)
	v_add_u32_e32 v36, 0xa0, v146
	v_cmp_lt_i32_e32 vcc, s16, v146
	s_and_saveexec_b64 s[16:17], vcc
	s_xor_b64 s[16:17], exec, s[16:17]
	v_add_u32_e32 v38, 0xffff80a0, v146
	v_mov_b32_e32 v39, v2
	v_lshlrev_b64 v[38:39], 12, v[38:39]
	v_lshl_add_u64 v[38:39], s[10:11], 0, v[38:39]
	v_mov_b32_e32 v37, v2
	s_andn2_saveexec_b64 s[16:17], s[16:17]
	v_ashrrev_i32_e32 v37, 31, v36
	v_lshlrev_b64 v[38:39], 12, v[36:37]
	v_lshl_add_u64 v[38:39], s[30:31], 0, v[38:39]
	s_or_b64 exec, exec, s[16:17]
	v_lshl_add_u64 v[46:47], v[38:39], 0, v[144:145]
	global_load_dwordx4 v[38:41], v[46:47], off
	global_load_dwordx4 v[42:45], v[46:47], off offset:16
	global_load_dwordx4 v[216:219], v[46:47], off offset:512
	global_load_dwordx4 v[220:223], v[46:47], off offset:528
	v_lshlrev_b64 v[48:49], 12, v[36:37]
	v_lshlrev_b64 v[50:51], 11, v[36:37]
	v_lshl_add_u64 v[48:49], s[30:31], 0, v[48:49]
	v_lshl_add_u64 v[50:51], s[18:19], 0, v[50:51]
	v_lshl_add_u64 v[48:49], v[48:49], 0, v[144:145]
	v_lshl_add_u64 v[50:51], v[142:143], 1, v[50:51]
	s_waitcnt vmcnt(3)
	v_pk_add_f32 v[34:35], v[40:41], v[34:35]
	v_pk_add_f32 v[32:33], v[38:39], v[32:33]
	s_waitcnt vmcnt(2)
	v_pk_add_f32 v[30:31], v[44:45], v[30:31]
	v_pk_add_f32 v[28:29], v[42:43], v[28:29]
	v_cvt_pk_bf16_f32 v38, v32, v33
	v_cvt_pk_bf16_f32 v39, v34, v35
	v_cvt_pk_bf16_f32 v40, v28, v29
	v_cvt_pk_bf16_f32 v41, v30, v31
	global_store_dwordx4 v[48:49], v[32:35], off
	global_store_dwordx4 v[48:49], v[28:31], off offset:16
	global_store_dwordx4 v[50:51], v[38:41], off
	s_nop 0
	s_nop 0
	s_nop 0
	v_mul_f32_e32 v33, v33, v33
	v_mul_f32_e32 v35, v35, v35
	v_mul_f32_e32 v29, v29, v29
	v_fmac_f32_e32 v33, v32, v32
	v_fmac_f32_e32 v35, v34, v34
	v_mul_f32_e32 v31, v31, v31
	v_fmac_f32_e32 v29, v28, v28
	v_add_f32_e32 v28, v33, v35
	v_fmac_f32_e32 v31, v30, v30
	v_add_f32_e32 v28, v29, v28
	v_add_f32_e32 v32, v31, v28
	s_waitcnt vmcnt(4)
	v_pk_add_f32 v[26:27], v[218:219], v[26:27]
	v_pk_add_f32 v[24:25], v[216:217], v[24:25]
	s_waitcnt vmcnt(3)
	v_pk_add_f32 v[28:29], v[220:221], v[20:21]
	v_mul_f32_e32 v20, v25, v25
	v_mul_f32_e32 v21, v27, v27
	v_pk_add_f32 v[30:31], v[222:223], v[22:23]
	v_mul_f32_e32 v22, v29, v29
	v_fmac_f32_e32 v20, v24, v24
	v_fmac_f32_e32 v21, v26, v26
	v_mul_f32_e32 v23, v31, v31
	v_fmac_f32_e32 v22, v28, v28
	v_add_f32_e32 v20, v20, v21
	v_add_f32_e32 v20, v22, v20
	v_fmac_f32_e32 v23, v30, v30
	v_add_f32_e32 v20, v23, v20
	v_add_f32_e32 v20, v32, v20
	ds_bpermute_b32 v21, v3, v20
	global_store_dwordx4 v[48:49], v[24:27], off offset:512
	global_store_dwordx4 v[48:49], v[28:31], off offset:528
	v_cvt_pk_bf16_f32 v22, v24, v25
	v_cvt_pk_bf16_f32 v23, v26, v27
	v_cvt_pk_bf16_f32 v24, v28, v29
	s_waitcnt lgkmcnt(0)
	v_add_f32_e32 v20, v20, v21
	ds_bpermute_b32 v21, v120, v20
	v_cvt_pk_bf16_f32 v25, v30, v31
	global_store_dwordx4 v[50:51], v[22:25], off offset:256
	s_and_saveexec_b64 s[16:17], s[6:7]
	s_cbranch_execz .LBB0_1437
	s_waitcnt lgkmcnt(0)
	v_add_f32_e32 v22, v20, v21
	v_lshl_add_u64 v[20:21], v[36:37], 2, s[12:13]
	v_mov_b32_e32 v248, v20
	v_mov_b32_e32 v249, v21
	v_mov_b32_e32 v250, v22
.LBB0_1437:
	s_or_b64 exec, exec, s[16:17]
	s_movk_i32 s16, 0x7f4f
	s_waitcnt lgkmcnt(0)
	v_add_u32_e32 v20, 0xb0, v146
	v_cmp_lt_i32_e32 vcc, s16, v146
	s_and_saveexec_b64 s[16:17], vcc
	s_xor_b64 s[16:17], exec, s[16:17]
	v_add_u32_e32 v22, 0xffff80b0, v146
	v_mov_b32_e32 v23, v2
	v_lshlrev_b64 v[22:23], 12, v[22:23]
	v_lshl_add_u64 v[22:23], s[10:11], 0, v[22:23]
	v_mov_b32_e32 v21, v2
	s_andn2_saveexec_b64 s[16:17], s[16:17]
	v_ashrrev_i32_e32 v21, 31, v20
	v_lshlrev_b64 v[22:23], 12, v[20:21]
	v_lshl_add_u64 v[22:23], s[30:31], 0, v[22:23]
	s_or_b64 exec, exec, s[16:17]
	v_lshl_add_u64 v[30:31], v[22:23], 0, v[144:145]
	global_load_dwordx4 v[22:25], v[30:31], off
	global_load_dwordx4 v[26:29], v[30:31], off offset:16
	global_load_dwordx4 v[216:219], v[30:31], off offset:512
	global_load_dwordx4 v[220:223], v[30:31], off offset:528
	v_lshlrev_b64 v[32:33], 12, v[20:21]
	v_lshlrev_b64 v[34:35], 11, v[20:21]
	v_lshl_add_u64 v[32:33], s[30:31], 0, v[32:33]
	v_lshl_add_u64 v[34:35], s[18:19], 0, v[34:35]
	v_lshl_add_u64 v[32:33], v[32:33], 0, v[144:145]
	v_lshl_add_u64 v[34:35], v[142:143], 1, v[34:35]
	s_waitcnt vmcnt(3)
	v_pk_add_f32 v[18:19], v[24:25], v[18:19]
	v_pk_add_f32 v[16:17], v[22:23], v[16:17]
	s_waitcnt vmcnt(2)
	v_pk_add_f32 v[14:15], v[28:29], v[14:15]
	v_pk_add_f32 v[12:13], v[26:27], v[12:13]
	v_cvt_pk_bf16_f32 v22, v16, v17
	v_cvt_pk_bf16_f32 v23, v18, v19
	v_cvt_pk_bf16_f32 v24, v12, v13
	v_cvt_pk_bf16_f32 v25, v14, v15
	global_store_dwordx4 v[32:33], v[16:19], off
	global_store_dwordx4 v[32:33], v[12:15], off offset:16
	global_store_dwordx4 v[34:35], v[22:25], off
	s_nop 0
	s_nop 0
	s_nop 0
	v_mul_f32_e32 v17, v17, v17
	v_mul_f32_e32 v19, v19, v19
	v_mul_f32_e32 v13, v13, v13
	v_fmac_f32_e32 v17, v16, v16
	v_fmac_f32_e32 v19, v18, v18
	v_mul_f32_e32 v15, v15, v15
	v_fmac_f32_e32 v13, v12, v12
	v_add_f32_e32 v12, v17, v19
	v_fmac_f32_e32 v15, v14, v14
	v_add_f32_e32 v12, v13, v12
	v_add_f32_e32 v16, v15, v12
	s_waitcnt vmcnt(4)
	v_pk_add_f32 v[10:11], v[218:219], v[10:11]
	v_pk_add_f32 v[8:9], v[216:217], v[8:9]
	s_waitcnt vmcnt(3)
	v_pk_add_f32 v[12:13], v[220:221], v[4:5]
	v_mul_f32_e32 v4, v9, v9
	v_mul_f32_e32 v5, v11, v11
	v_pk_add_f32 v[14:15], v[222:223], v[6:7]
	v_mul_f32_e32 v6, v13, v13
	v_fmac_f32_e32 v4, v8, v8
	v_fmac_f32_e32 v5, v10, v10
	v_mul_f32_e32 v7, v15, v15
	v_fmac_f32_e32 v6, v12, v12
	v_add_f32_e32 v4, v4, v5
	v_add_f32_e32 v4, v6, v4
	v_fmac_f32_e32 v7, v14, v14
	v_add_f32_e32 v4, v7, v4
	v_add_f32_e32 v4, v16, v4
	ds_bpermute_b32 v3, v3, v4
	global_store_dwordx4 v[32:33], v[8:11], off offset:512
	global_store_dwordx4 v[32:33], v[12:15], off offset:528
	v_cvt_pk_bf16_f32 v6, v8, v9
	v_cvt_pk_bf16_f32 v7, v10, v11
	v_cvt_pk_bf16_f32 v8, v12, v13
	s_waitcnt lgkmcnt(0)
	v_add_f32_e32 v3, v4, v3
	ds_bpermute_b32 v4, v120, v3
	v_cvt_pk_bf16_f32 v9, v14, v15
	global_store_dwordx4 v[34:35], v[6:9], off offset:256
	s_and_saveexec_b64 s[16:17], s[6:7]
	s_cbranch_execz .LBB0_1443
	s_waitcnt lgkmcnt(0)
	v_add_f32_e32 v3, v3, v4
	v_lshl_add_u64 v[4:5], v[20:21], 2, s[12:13]
	global_atomic_add_f32 v[4:5], v3, off
	global_atomic_add_f32 v[224:225], v226, off
	global_atomic_add_f32 v[228:229], v230, off
	global_atomic_add_f32 v[232:233], v234, off
	global_atomic_add_f32 v[236:237], v238, off
	global_atomic_add_f32 v[240:241], v242, off
	global_atomic_add_f32 v[244:245], v246, off
	global_atomic_add_f32 v[248:249], v250, off

; template <class Epi>
; __device__ __forceinline__ void gemm_phase(LAS unsigned char* lds, const Gemm g, const StaticOrder& S, const Epi& E) {
;     ...
;                 for (int sl = 0; sl < S.NS; ++sl) { if (sl == myslice) continue;
;                     const __amdgpu_buffer_rsrc_t qrs = __builtin_amdgcn_make_buffer_rsrc((void*)(T + (size_t)sl * 65536), 0, 262144, 0x00020000);
; #pragma unroll
;                     for (int a = 0; a < 2; ++a)
; #pragma unroll
;                         for (int m = 0; m < 4; ++m)
; #pragma unroll
;                             for (int b = 0; b < 2; ++b)
; #pragma unroll
;                                 for (int n = 0; n < 2; ++n) acc[a][b][m][n] += __builtin_bit_cast(f32x4, __builtin_amdgcn_raw_buffer_load_b128(qrs, (int)(toff + (((a * 4 + m) * 2 + b) * 2 + n) * 8192), 0, 16)); }
.LBB0_1615:
	s_lshl_b32 s16, s16, 18
	s_add_u32 s16, s37, s16
	s_addc_u32 s17, s77, 0
	s_and_b32 s17, s17, 0xffff
	buffer_load_dwordx4 v[196:199], v141, s[16:19], 0 offen sc1
	buffer_load_dwordx4 v[200:203], v152, s[16:19], 0 offen sc1
	buffer_load_dwordx4 v[204:207], v156, s[16:19], 0 offen sc1
	buffer_load_dwordx4 v[208:211], v157, s[16:19], 0 offen sc1
	buffer_load_dwordx4 v[212:215], v160, s[16:19], 0 offen sc1
	buffer_load_dwordx4 v[216:219], v161, s[16:19], 0 offen sc1
	buffer_load_dwordx4 v[220:223], v162, s[16:19], 0 offen sc1
	buffer_load_dwordx4 v[224:227], v163, s[16:19], 0 offen sc1
	s_waitcnt vmcnt(7)
	v_pk_add_f32 v[130:131], v[130:131], v[198:199]
	v_pk_add_f32 v[128:129], v[128:129], v[196:197]
	buffer_load_dwordx4 v[196:199], v164, s[16:19], 0 offen sc1
	s_waitcnt vmcnt(7)
	v_pk_add_f32 v[126:127], v[126:127], v[202:203]
	v_pk_add_f32 v[124:125], v[124:125], v[200:201]
	buffer_load_dwordx4 v[200:203], v165, s[16:19], 0 offen sc1
	s_waitcnt vmcnt(7)
	v_pk_add_f32 v[122:123], v[122:123], v[206:207]
	v_pk_add_f32 v[120:121], v[120:121], v[204:205]
	buffer_load_dwordx4 v[204:207], v166, s[16:19], 0 offen sc1
	s_waitcnt vmcnt(7)
	v_pk_add_f32 v[118:119], v[118:119], v[210:211]
	v_pk_add_f32 v[116:117], v[116:117], v[208:209]
	buffer_load_dwordx4 v[208:211], v167, s[16:19], 0 offen sc1
	s_waitcnt vmcnt(7)
	v_pk_add_f32 v[114:115], v[114:115], v[214:215]
	v_pk_add_f32 v[112:113], v[112:113], v[212:213]
	buffer_load_dwordx4 v[212:215], v168, s[16:19], 0 offen sc1
	s_waitcnt vmcnt(7)
	v_pk_add_f32 v[110:111], v[110:111], v[218:219]
	v_pk_add_f32 v[108:109], v[108:109], v[216:217]
	buffer_load_dwordx4 v[216:219], v169, s[16:19], 0 offen sc1
	s_waitcnt vmcnt(7)
	v_pk_add_f32 v[106:107], v[106:107], v[222:223]
	v_pk_add_f32 v[104:105], v[104:105], v[220:221]
	buffer_load_dwordx4 v[220:223], v170, s[16:19], 0 offen sc1
	s_waitcnt vmcnt(7)
	v_pk_add_f32 v[102:103], v[102:103], v[226:227]
	v_pk_add_f32 v[100:101], v[100:101], v[224:225]
	buffer_load_dwordx4 v[224:227], v171, s[16:19], 0 offen sc1
	s_waitcnt vmcnt(7)
	v_pk_add_f32 v[98:99], v[98:99], v[198:199]
	v_pk_add_f32 v[96:97], v[96:97], v[196:197]
	buffer_load_dwordx4 v[196:199], v172, s[16:19], 0 offen sc1
	s_waitcnt vmcnt(7)
	v_pk_add_f32 v[94:95], v[94:95], v[202:203]
	v_pk_add_f32 v[92:93], v[92:93], v[200:201]
	buffer_load_dwordx4 v[200:203], v173, s[16:19], 0 offen sc1
	s_waitcnt vmcnt(7)
	v_pk_add_f32 v[90:91], v[90:91], v[206:207]
	v_pk_add_f32 v[88:89], v[88:89], v[204:205]
	buffer_load_dwordx4 v[204:207], v174, s[16:19], 0 offen sc1
	s_waitcnt vmcnt(7)
	v_pk_add_f32 v[86:87], v[86:87], v[210:211]
	v_pk_add_f32 v[84:85], v[84:85], v[208:209]
	buffer_load_dwordx4 v[208:211], v175, s[16:19], 0 offen sc1
	s_waitcnt vmcnt(7)
	v_pk_add_f32 v[82:83], v[82:83], v[214:215]
	v_pk_add_f32 v[80:81], v[80:81], v[212:213]
	buffer_load_dwordx4 v[212:215], v176, s[16:19], 0 offen sc1
	s_waitcnt vmcnt(7)
	v_pk_add_f32 v[78:79], v[78:79], v[218:219]
	v_pk_add_f32 v[76:77], v[76:77], v[216:217]
	buffer_load_dwordx4 v[216:219], v177, s[16:19], 0 offen sc1
	s_waitcnt vmcnt(7)
	v_pk_add_f32 v[74:75], v[74:75], v[222:223]
	v_pk_add_f32 v[72:73], v[72:73], v[220:221]
	buffer_load_dwordx4 v[220:223], v178, s[16:19], 0 offen sc1
	s_waitcnt vmcnt(7)
	v_pk_add_f32 v[70:71], v[70:71], v[226:227]
	v_pk_add_f32 v[68:69], v[68:69], v[224:225]
	buffer_load_dwordx4 v[224:227], v179, s[16:19], 0 offen sc1
	s_waitcnt vmcnt(7)
	v_pk_add_f32 v[66:67], v[66:67], v[198:199]
	v_pk_add_f32 v[64:65], v[64:65], v[196:197]
	buffer_load_dwordx4 v[196:199], v180, s[16:19], 0 offen sc1
	s_waitcnt vmcnt(7)
	v_pk_add_f32 v[62:63], v[62:63], v[202:203]
	v_pk_add_f32 v[60:61], v[60:61], v[200:201]
	buffer_load_dwordx4 v[200:203], v181, s[16:19], 0 offen sc1
	s_waitcnt vmcnt(7)
	v_pk_add_f32 v[58:59], v[58:59], v[206:207]
	v_pk_add_f32 v[56:57], v[56:57], v[204:205]
	buffer_load_dwordx4 v[204:207], v182, s[16:19], 0 offen sc1
	s_waitcnt vmcnt(7)
	v_pk_add_f32 v[54:55], v[54:55], v[210:211]
	v_pk_add_f32 v[52:53], v[52:53], v[208:209]
	buffer_load_dwordx4 v[208:211], v183, s[16:19], 0 offen sc1
	s_waitcnt vmcnt(7)
	v_pk_add_f32 v[50:51], v[50:51], v[214:215]
	v_pk_add_f32 v[48:49], v[48:49], v[212:213]
	buffer_load_dwordx4 v[212:215], v184, s[16:19], 0 offen sc1
	s_waitcnt vmcnt(7)
	v_pk_add_f32 v[46:47], v[46:47], v[218:219]
	v_pk_add_f32 v[44:45], v[44:45], v[216:217]
	buffer_load_dwordx4 v[216:219], v185, s[16:19], 0 offen sc1
	s_waitcnt vmcnt(7)
	v_pk_add_f32 v[42:43], v[42:43], v[222:223]
	v_pk_add_f32 v[40:41], v[40:41], v[220:221]
	buffer_load_dwordx4 v[220:223], v186, s[16:19], 0 offen sc1
	s_waitcnt vmcnt(7)
	v_pk_add_f32 v[38:39], v[38:39], v[226:227]
	v_pk_add_f32 v[36:37], v[36:37], v[224:225]
	buffer_load_dwordx4 v[224:227], v187, s[16:19], 0 offen sc1
	s_waitcnt vmcnt(7)
	v_pk_add_f32 v[34:35], v[34:35], v[198:199]
	v_pk_add_f32 v[32:33], v[32:33], v[196:197]
	s_waitcnt vmcnt(6)
	v_pk_add_f32 v[30:31], v[30:31], v[202:203]
	v_pk_add_f32 v[28:29], v[28:29], v[200:201]
	s_waitcnt vmcnt(5)
	v_pk_add_f32 v[26:27], v[26:27], v[206:207]
	v_pk_add_f32 v[24:25], v[24:25], v[204:205]
	s_waitcnt vmcnt(4)
	v_pk_add_f32 v[22:23], v[22:23], v[210:211]
	v_pk_add_f32 v[20:21], v[20:21], v[208:209]
	s_waitcnt vmcnt(3)
	v_pk_add_f32 v[18:19], v[18:19], v[214:215]
	v_pk_add_f32 v[16:17], v[16:17], v[212:213]
	s_waitcnt vmcnt(2)
	v_pk_add_f32 v[14:15], v[14:15], v[218:219]
	v_pk_add_f32 v[12:13], v[12:13], v[216:217]
	s_waitcnt vmcnt(1)
	v_pk_add_f32 v[10:11], v[10:11], v[222:223]
	v_pk_add_f32 v[8:9], v[8:9], v[220:221]
	s_waitcnt vmcnt(0)
	v_pk_add_f32 v[6:7], v[6:7], v[226:227]
	v_pk_add_f32 v[4:5], v[4:5], v[224:225]

; __device__ __forceinline__ u32x4 pack8(f32x4 a, f32x4 b) { u32x4 w; w.x = pk2(a[0], a[1]); w.y = pk2(a[2], a[3]); w.z = pk2(b[0], b[1]); w.w = pk2(b[2], b[3]); return w; }
; __device__ __forceinline__ float dot8(f32x4 a, f32x4 b) { return (a[0] * a[0] + a[1] * a[1]) + (a[2] * a[2] + a[3] * a[3]) + (b[0] * b[0] + b[1] * b[1]) + (b[2] * b[2] + b[3] * b[3]); }
; __device__ __forceinline__ float red_fq(float s) { s += __shfl_xor(s, 16); s += __shfl_xor(s, 32); return s; }
;     __device__ __forceinline__ void operator()(AccRef acc, const Unit& u, int wr, int wc, int fr, int fq) const {
;     ...
;             const float* rp = (row < MP) ? res0 + (size_t)row * DM : res1 + (size_t)(row - MP) * DM;
;             float s = 0.f;
;             _Pragma("unroll") for (int bj = 0; bj < 2; ++bj) { const int col = col0 + bj * 128;
;                 f32x4 v0 = *(const f32x4*)(rp + col) + acc[ai][bj][m][0] * scale, v1 = *(const f32x4*)(rp + col + 4) + acc[ai][bj][m][1] * scale;
;                 *(f32x4*)(out + (size_t)row * DM + col) = v0; *(f32x4*)(out + (size_t)row * DM + col + 4) = v1;
;                 if (WB) *(u32x4*)(ob + (size_t)row * DM + col) = pack8(v0, v1);
;                 s += dot8(v0, v1); }
;             s = red_fq(s); if (fq == 0) unsafeAtomicAdd(ss + row, s);
.LBB0_1624:
	v_lshl_add_u32 v142, s76, 8, v155
	v_cmp_lt_i32_e32 vcc, s67, v142
	s_and_saveexec_b64 s[16:17], vcc
	s_xor_b64 s[16:17], exec, s[16:17]
	v_add_u32_e32 v144, 0xffff8000, v142
	v_mov_b32_e32 v145, v2
	v_lshlrev_b64 v[144:145], 12, v[144:145]
	v_mov_b32_e32 v143, v2
	v_lshl_add_u64 v[148:149], s[10:11], 0, v[144:145]
	v_lshlrev_b64 v[146:147], 12, v[142:143]
	s_andn2_saveexec_b64 s[16:17], s[16:17]
	v_ashrrev_i32_e32 v143, 31, v142
	v_lshlrev_b64 v[146:147], 12, v[142:143]
	v_lshl_add_u64 v[148:149], s[30:31], 0, v[146:147]
	s_or_b64 exec, exec, s[16:17]
	v_lshl_or_b32 v144, s75, 8, v188
	v_ashrrev_i32_e32 v145, 31, v144
	v_lshlrev_b64 v[144:145], 2, v[144:145]
	v_lshl_add_u64 v[202:203], v[148:149], 0, v[144:145]
	global_load_dwordx4 v[194:197], v[202:203], off
	global_load_dwordx4 v[198:201], v[202:203], off offset:16
	global_load_dwordx4 v[216:219], v[202:203], off offset:512
	global_load_dwordx4 v[220:223], v[202:203], off offset:528
	v_lshl_add_u64 v[146:147], s[30:31], 0, v[146:147]
	v_lshl_add_u64 v[204:205], v[146:147], 0, v[144:145]
	v_and_b32_e32 v158, 64, v159
	v_xor_b32_e32 v3, 16, v159
	v_add_u32_e32 v158, 64, v158
	v_cmp_lt_i32_e32 vcc, v3, v158
	s_waitcnt vmcnt(3)
	v_pk_fma_f32 v[130:131], v[130:131], 0.5, v[196:197] op_sel_hi:[1,0,1]
	v_pk_fma_f32 v[128:129], v[128:129], 0.5, v[194:195] op_sel_hi:[1,0,1]
	s_waitcnt vmcnt(2)
	v_pk_fma_f32 v[126:127], v[126:127], 0.5, v[200:201] op_sel_hi:[1,0,1]
	v_pk_fma_f32 v[124:125], v[124:125], 0.5, v[198:199] op_sel_hi:[1,0,1]
	global_store_dwordx4 v[204:205], v[128:131], off
	global_store_dwordx4 v[204:205], v[124:127], off offset:16
	s_nop 0
	s_nop 0
	v_mul_f32_e32 v129, v129, v129
	v_mul_f32_e32 v131, v131, v131
	v_mul_f32_e32 v125, v125, v125
	v_fmac_f32_e32 v129, v128, v128
	v_fmac_f32_e32 v131, v130, v130
	v_mul_f32_e32 v127, v127, v127
	v_fmac_f32_e32 v125, v124, v124
	v_add_f32_e32 v124, v129, v131
	v_fmac_f32_e32 v127, v126, v126
	v_add_f32_e32 v124, v125, v124
	v_add_f32_e32 v128, v127, v124
	v_cndmask_b32_e32 v3, v159, v3, vcc
	v_lshlrev_b32_e32 v3, 2, v3
	s_waitcnt vmcnt(3)
	v_pk_fma_f32 v[126:127], v[122:123], 0.5, v[218:219] op_sel_hi:[1,0,1]
	v_pk_fma_f32 v[124:125], v[120:121], 0.5, v[216:217] op_sel_hi:[1,0,1]
	s_waitcnt vmcnt(2)
	v_pk_fma_f32 v[120:121], v[118:119], 0.5, v[222:223] op_sel_hi:[1,0,1]
	v_pk_fma_f32 v[118:119], v[116:117], 0.5, v[220:221] op_sel_hi:[1,0,1]
	v_mul_f32_e32 v116, v125, v125
	v_mul_f32_e32 v117, v127, v127
	v_mul_f32_e32 v122, v119, v119
	v_fmac_f32_e32 v116, v124, v124
	v_fmac_f32_e32 v117, v126, v126
	v_mul_f32_e32 v123, v121, v121
	v_fmac_f32_e32 v122, v118, v118
	v_add_f32_e32 v116, v116, v117
	v_add_f32_e32 v116, v122, v116
	v_fmac_f32_e32 v123, v120, v120
	v_add_f32_e32 v116, v123, v116
	v_add_f32_e32 v116, v128, v116
	ds_bpermute_b32 v117, v3, v116
	v_xor_b32_e32 v122, 32, v159
	v_cmp_lt_i32_e32 vcc, v122, v158
	global_store_dwordx4 v[204:205], v[124:127], off offset:512
	global_store_dwordx4 v[204:205], v[118:121], off offset:528
	v_cndmask_b32_e32 v122, v159, v122, vcc
	v_lshlrev_b32_e32 v122, 2, v122
	s_waitcnt lgkmcnt(0)
	v_add_f32_e32 v116, v116, v117
	ds_bpermute_b32 v117, v122, v116
	s_and_saveexec_b64 s[16:17], s[4:5]
	s_cbranch_execz .LBB0_1630
	s_waitcnt lgkmcnt(0)
	v_add_f32_e32 v118, v116, v117
	v_lshl_add_u64 v[116:117], v[142:143], 2, s[20:21]
	v_mov_b32_e32 v224, v116
	v_mov_b32_e32 v225, v117
	v_mov_b32_e32 v226, v118
.LBB0_1630:
	s_or_b64 exec, exec, s[16:17]
	s_waitcnt lgkmcnt(0)
	v_or_b32_e32 v116, 16, v142
	v_cmp_lt_i32_e32 vcc, s67, v116
	s_and_saveexec_b64 s[16:17], vcc
	s_xor_b64 s[16:17], exec, s[16:17]
	v_add_u32_e32 v118, 0xffff8010, v142
	v_mov_b32_e32 v119, v2
	v_lshlrev_b64 v[118:119], 12, v[118:119]
	v_mov_b32_e32 v117, v2
	v_lshl_add_u64 v[120:121], s[10:11], 0, v[118:119]
	v_lshlrev_b64 v[118:119], 12, v[116:117]
	s_andn2_saveexec_b64 s[16:17], s[16:17]
	v_ashrrev_i32_e32 v117, 31, v116
	v_lshlrev_b64 v[118:119], 12, v[116:117]
	v_lshl_add_u64 v[120:121], s[30:31], 0, v[118:119]
	s_or_b64 exec, exec, s[16:17]
	v_lshl_add_u64 v[146:147], v[120:121], 0, v[144:145]
	global_load_dwordx4 v[124:127], v[146:147], off
	global_load_dwordx4 v[128:131], v[146:147], off offset:16
	global_load_dwordx4 v[216:219], v[146:147], off offset:512
	global_load_dwordx4 v[220:223], v[146:147], off offset:528
	v_lshl_add_u64 v[118:119], s[30:31], 0, v[118:119]
	v_lshl_add_u64 v[148:149], v[118:119], 0, v[144:145]
	s_waitcnt vmcnt(3)
	v_pk_fma_f32 v[114:115], v[114:115], 0.5, v[126:127] op_sel_hi:[1,0,1]
	v_pk_fma_f32 v[112:113], v[112:113], 0.5, v[124:125] op_sel_hi:[1,0,1]
	s_waitcnt vmcnt(2)
	v_pk_fma_f32 v[110:111], v[110:111], 0.5, v[130:131] op_sel_hi:[1,0,1]
	v_pk_fma_f32 v[108:109], v[108:109], 0.5, v[128:129] op_sel_hi:[1,0,1]
	global_store_dwordx4 v[148:149], v[112:115], off
	global_store_dwordx4 v[148:149], v[108:111], off offset:16
	s_nop 0
	s_nop 0
	v_mul_f32_e32 v113, v113, v113
	v_mul_f32_e32 v115, v115, v115
	v_mul_f32_e32 v109, v109, v109
	v_fmac_f32_e32 v113, v112, v112
	v_fmac_f32_e32 v115, v114, v114
	v_mul_f32_e32 v111, v111, v111
	v_fmac_f32_e32 v109, v108, v108
	v_add_f32_e32 v108, v113, v115
	v_fmac_f32_e32 v111, v110, v110
	v_add_f32_e32 v108, v109, v108
	v_add_f32_e32 v112, v111, v108
	s_waitcnt vmcnt(3)
	v_pk_fma_f32 v[106:107], v[106:107], 0.5, v[218:219] op_sel_hi:[1,0,1]
	v_pk_fma_f32 v[104:105], v[104:105], 0.5, v[216:217] op_sel_hi:[1,0,1]
	s_waitcnt vmcnt(2)
	v_pk_fma_f32 v[108:109], v[100:101], 0.5, v[220:221] op_sel_hi:[1,0,1]
	v_mul_f32_e32 v100, v105, v105
	v_mul_f32_e32 v101, v107, v107
	v_pk_fma_f32 v[110:111], v[102:103], 0.5, v[222:223] op_sel_hi:[1,0,1]
	v_mul_f32_e32 v102, v109, v109
	v_fmac_f32_e32 v100, v104, v104
	v_fmac_f32_e32 v101, v106, v106
	v_mul_f32_e32 v103, v111, v111
	v_fmac_f32_e32 v102, v108, v108
	v_add_f32_e32 v100, v100, v101
	v_add_f32_e32 v100, v102, v100
	v_fmac_f32_e32 v103, v110, v110
	v_add_f32_e32 v100, v103, v100
	v_add_f32_e32 v100, v112, v100
	ds_bpermute_b32 v101, v3, v100
	global_store_dwordx4 v[148:149], v[104:107], off offset:512
	global_store_dwordx4 v[148:149], v[108:111], off offset:528
	s_waitcnt lgkmcnt(0)
	v_add_f32_e32 v100, v100, v101
	ds_bpermute_b32 v101, v122, v100
	s_and_saveexec_b64 s[16:17], s[4:5]
	s_cbranch_execz .LBB0_1636
	s_waitcnt lgkmcnt(0)
	v_add_f32_e32 v102, v100, v101
	v_lshl_add_u64 v[100:101], v[116:117], 2, s[20:21]
	v_mov_b32_e32 v228, v100
	v_mov_b32_e32 v229, v101
	v_mov_b32_e32 v230, v102
; __device__ __forceinline__ u32x4 pack8(f32x4 a, f32x4 b) { u32x4 w; w.x = pk2(a[0], a[1]); w.y = pk2(a[2], a[3]); w.z = pk2(b[0], b[1]); w.w = pk2(b[2], b[3]); return w; }
; __device__ __forceinline__ float dot8(f32x4 a, f32x4 b) { return (a[0] * a[0] + a[1] * a[1]) + (a[2] * a[2] + a[3] * a[3]) + (b[0] * b[0] + b[1] * b[1]) + (b[2] * b[2] + b[3] * b[3]); }
; __device__ __forceinline__ float red_fq(float s) { s += __shfl_xor(s, 16); s += __shfl_xor(s, 32); return s; }
;     __device__ __forceinline__ void operator()(AccRef acc, const Unit& u, int wr, int wc, int fr, int fq) const {
;     ...
;             const float* rp = (row < MP) ? res0 + (size_t)row * DM : res1 + (size_t)(row - MP) * DM;
;             float s = 0.f;
;             _Pragma("unroll") for (int bj = 0; bj < 2; ++bj) { const int col = col0 + bj * 128;
;                 f32x4 v0 = *(const f32x4*)(rp + col) + acc[ai][bj][m][0] * scale, v1 = *(const f32x4*)(rp + col + 4) + acc[ai][bj][m][1] * scale;
;                 *(f32x4*)(out + (size_t)row * DM + col) = v0; *(f32x4*)(out + (size_t)row * DM + col + 4) = v1;
;                 if (WB) *(u32x4*)(ob + (size_t)row * DM + col) = pack8(v0, v1);
;                 s += dot8(v0, v1); }
;             s = red_fq(s); if (fq == 0) unsafeAtomicAdd(ss + row, s);
.LBB0_1636:
	s_or_b64 exec, exec, s[16:17]
	s_waitcnt lgkmcnt(0)
	v_or_b32_e32 v100, 32, v142
	v_cmp_lt_i32_e32 vcc, s67, v100
	s_and_saveexec_b64 s[16:17], vcc
	s_xor_b64 s[16:17], exec, s[16:17]
	v_add_u32_e32 v102, 0xffff8020, v142
	v_mov_b32_e32 v103, v2
	v_lshlrev_b64 v[102:103], 12, v[102:103]
	v_mov_b32_e32 v101, v2
	v_lshl_add_u64 v[104:105], s[10:11], 0, v[102:103]
	v_lshlrev_b64 v[102:103], 12, v[100:101]
	s_andn2_saveexec_b64 s[16:17], s[16:17]
	v_ashrrev_i32_e32 v101, 31, v100
	v_lshlrev_b64 v[102:103], 12, v[100:101]
	v_lshl_add_u64 v[104:105], s[30:31], 0, v[102:103]
	s_or_b64 exec, exec, s[16:17]
	v_lshl_add_u64 v[112:113], v[104:105], 0, v[144:145]
	global_load_dwordx4 v[104:107], v[112:113], off
	global_load_dwordx4 v[108:111], v[112:113], off offset:16
	global_load_dwordx4 v[216:219], v[112:113], off offset:512
	global_load_dwordx4 v[220:223], v[112:113], off offset:528
	v_lshl_add_u64 v[102:103], s[30:31], 0, v[102:103]
	v_lshl_add_u64 v[114:115], v[102:103], 0, v[144:145]
	s_waitcnt vmcnt(3)
	v_pk_fma_f32 v[98:99], v[98:99], 0.5, v[106:107] op_sel_hi:[1,0,1]
	v_pk_fma_f32 v[96:97], v[96:97], 0.5, v[104:105] op_sel_hi:[1,0,1]
	s_waitcnt vmcnt(2)
	v_pk_fma_f32 v[94:95], v[94:95], 0.5, v[110:111] op_sel_hi:[1,0,1]
	v_pk_fma_f32 v[92:93], v[92:93], 0.5, v[108:109] op_sel_hi:[1,0,1]
	global_store_dwordx4 v[114:115], v[96:99], off
	global_store_dwordx4 v[114:115], v[92:95], off offset:16
	s_nop 0
	s_nop 0
	v_mul_f32_e32 v97, v97, v97
	v_mul_f32_e32 v99, v99, v99
	v_mul_f32_e32 v93, v93, v93
	v_fmac_f32_e32 v97, v96, v96
	v_fmac_f32_e32 v99, v98, v98
	v_mul_f32_e32 v95, v95, v95
	v_fmac_f32_e32 v93, v92, v92
	v_add_f32_e32 v92, v97, v99
	v_fmac_f32_e32 v95, v94, v94
	v_add_f32_e32 v92, v93, v92
	v_add_f32_e32 v96, v95, v92
	s_waitcnt vmcnt(3)
	v_pk_fma_f32 v[90:91], v[90:91], 0.5, v[218:219] op_sel_hi:[1,0,1]
	v_pk_fma_f32 v[88:89], v[88:89], 0.5, v[216:217] op_sel_hi:[1,0,1]
	s_waitcnt vmcnt(2)
	v_pk_fma_f32 v[92:93], v[84:85], 0.5, v[220:221] op_sel_hi:[1,0,1]
	v_mul_f32_e32 v84, v89, v89
	v_mul_f32_e32 v85, v91, v91
	v_pk_fma_f32 v[94:95], v[86:87], 0.5, v[222:223] op_sel_hi:[1,0,1]
	v_mul_f32_e32 v86, v93, v93
	v_fmac_f32_e32 v84, v88, v88
	v_fmac_f32_e32 v85, v90, v90
	v_mul_f32_e32 v87, v95, v95
	v_fmac_f32_e32 v86, v92, v92
	v_add_f32_e32 v84, v84, v85
	v_add_f32_e32 v84, v86, v84
	v_fmac_f32_e32 v87, v94, v94
	v_add_f32_e32 v84, v87, v84
	v_add_f32_e32 v84, v96, v84
	ds_bpermute_b32 v85, v3, v84
	global_store_dwordx4 v[114:115], v[88:91], off offset:512
	global_store_dwordx4 v[114:115], v[92:95], off offset:528
	s_waitcnt lgkmcnt(0)
	v_add_f32_e32 v84, v84, v85
	ds_bpermute_b32 v85, v122, v84
	s_and_saveexec_b64 s[16:17], s[4:5]
	s_cbranch_execz .LBB0_1642
	s_waitcnt lgkmcnt(0)
	v_add_f32_e32 v86, v84, v85
	v_lshl_add_u64 v[84:85], v[100:101], 2, s[20:21]
	v_mov_b32_e32 v232, v84
	v_mov_b32_e32 v233, v85
	v_mov_b32_e32 v234, v86
.LBB0_1642:
	s_or_b64 exec, exec, s[16:17]
	s_waitcnt lgkmcnt(0)
	v_or_b32_e32 v84, 48, v142
	v_cmp_lt_i32_e32 vcc, s67, v84
	s_and_saveexec_b64 s[16:17], vcc
	s_xor_b64 s[16:17], exec, s[16:17]
	v_add_u32_e32 v86, 0xffff8030, v142
	v_mov_b32_e32 v87, v2
	v_lshlrev_b64 v[86:87], 12, v[86:87]
	v_mov_b32_e32 v85, v2
	v_lshl_add_u64 v[88:89], s[10:11], 0, v[86:87]
	v_lshlrev_b64 v[86:87], 12, v[84:85]
	s_andn2_saveexec_b64 s[16:17], s[16:17]
	v_ashrrev_i32_e32 v85, 31, v84
	v_lshlrev_b64 v[86:87], 12, v[84:85]
	v_lshl_add_u64 v[88:89], s[30:31], 0, v[86:87]
	s_or_b64 exec, exec, s[16:17]
	v_lshl_add_u64 v[96:97], v[88:89], 0, v[144:145]
	global_load_dwordx4 v[88:91], v[96:97], off
	global_load_dwordx4 v[92:95], v[96:97], off offset:16
	global_load_dwordx4 v[216:219], v[96:97], off offset:512
	global_load_dwordx4 v[220:223], v[96:97], off offset:528
	v_lshl_add_u64 v[86:87], s[30:31], 0, v[86:87]
	v_lshl_add_u64 v[98:99], v[86:87], 0, v[144:145]
	s_waitcnt vmcnt(3)
	v_pk_fma_f32 v[82:83], v[82:83], 0.5, v[90:91] op_sel_hi:[1,0,1]
	v_pk_fma_f32 v[80:81], v[80:81], 0.5, v[88:89] op_sel_hi:[1,0,1]
	s_waitcnt vmcnt(2)
	v_pk_fma_f32 v[78:79], v[78:79], 0.5, v[94:95] op_sel_hi:[1,0,1]
	v_pk_fma_f32 v[76:77], v[76:77], 0.5, v[92:93] op_sel_hi:[1,0,1]
	global_store_dwordx4 v[98:99], v[80:83], off
	global_store_dwordx4 v[98:99], v[76:79], off offset:16
	s_nop 0
	s_nop 0
	v_mul_f32_e32 v81, v81, v81
	v_mul_f32_e32 v83, v83, v83
	v_mul_f32_e32 v77, v77, v77
	v_fmac_f32_e32 v81, v80, v80
	v_fmac_f32_e32 v83, v82, v82
	v_mul_f32_e32 v79, v79, v79
	v_fmac_f32_e32 v77, v76, v76
	v_add_f32_e32 v76, v81, v83
	v_fmac_f32_e32 v79, v78, v78
	v_add_f32_e32 v76, v77, v76
	v_add_f32_e32 v80, v79, v76
	s_waitcnt vmcnt(3)
	v_pk_fma_f32 v[74:75], v[74:75], 0.5, v[218:219] op_sel_hi:[1,0,1]
	v_pk_fma_f32 v[72:73], v[72:73], 0.5, v[216:217] op_sel_hi:[1,0,1]
	s_waitcnt vmcnt(2)
	v_pk_fma_f32 v[76:77], v[68:69], 0.5, v[220:221] op_sel_hi:[1,0,1]
	v_mul_f32_e32 v68, v73, v73
	v_mul_f32_e32 v69, v75, v75
	v_pk_fma_f32 v[78:79], v[70:71], 0.5, v[222:223] op_sel_hi:[1,0,1]
	v_mul_f32_e32 v70, v77, v77
	v_fmac_f32_e32 v68, v72, v72
	v_fmac_f32_e32 v69, v74, v74
	v_mul_f32_e32 v71, v79, v79
	v_fmac_f32_e32 v70, v76, v76
	v_add_f32_e32 v68, v68, v69
	v_add_f32_e32 v68, v70, v68
	v_fmac_f32_e32 v71, v78, v78
	v_add_f32_e32 v68, v71, v68
	v_add_f32_e32 v68, v80, v68
	ds_bpermute_b32 v69, v3, v68
	global_store_dwordx4 v[98:99], v[72:75], off offset:512
	global_store_dwordx4 v[98:99], v[76:79], off offset:528
	s_waitcnt lgkmcnt(0)
	v_add_f32_e32 v68, v68, v69
	ds_bpermute_b32 v69, v122, v68
	s_and_saveexec_b64 s[16:17], s[4:5]
	s_cbranch_execz .LBB0_1648
	s_waitcnt lgkmcnt(0)
	v_add_f32_e32 v70, v68, v69
	v_lshl_add_u64 v[68:69], v[84:85], 2, s[20:21]
	v_mov_b32_e32 v236, v68
	v_mov_b32_e32 v237, v69
	v_mov_b32_e32 v238, v70
; __device__ __forceinline__ u32x4 pack8(f32x4 a, f32x4 b) { u32x4 w; w.x = pk2(a[0], a[1]); w.y = pk2(a[2], a[3]); w.z = pk2(b[0], b[1]); w.w = pk2(b[2], b[3]); return w; }
; __device__ __forceinline__ float dot8(f32x4 a, f32x4 b) { return (a[0] * a[0] + a[1] * a[1]) + (a[2] * a[2] + a[3] * a[3]) + (b[0] * b[0] + b[1] * b[1]) + (b[2] * b[2] + b[3] * b[3]); }
; __device__ __forceinline__ float red_fq(float s) { s += __shfl_xor(s, 16); s += __shfl_xor(s, 32); return s; }
;     __device__ __forceinline__ void operator()(AccRef acc, const Unit& u, int wr, int wc, int fr, int fq) const {
;     ...
;             const float* rp = (row < MP) ? res0 + (size_t)row * DM : res1 + (size_t)(row - MP) * DM;
;             float s = 0.f;
;             _Pragma("unroll") for (int bj = 0; bj < 2; ++bj) { const int col = col0 + bj * 128;
;                 f32x4 v0 = *(const f32x4*)(rp + col) + acc[ai][bj][m][0] * scale, v1 = *(const f32x4*)(rp + col + 4) + acc[ai][bj][m][1] * scale;
;                 *(f32x4*)(out + (size_t)row * DM + col) = v0; *(f32x4*)(out + (size_t)row * DM + col + 4) = v1;
;                 if (WB) *(u32x4*)(ob + (size_t)row * DM + col) = pack8(v0, v1);
;                 s += dot8(v0, v1); }
;             s = red_fq(s); if (fq == 0) unsafeAtomicAdd(ss + row, s);
.LBB0_1648:
	s_or_b64 exec, exec, s[16:17]
	s_waitcnt lgkmcnt(0)
	v_add_u32_e32 v68, 0x80, v142
	v_cmp_lt_i32_e32 vcc, s68, v142
	s_and_saveexec_b64 s[16:17], vcc
	s_xor_b64 s[16:17], exec, s[16:17]
	v_add_u32_e32 v70, 0xffff8080, v142
	v_mov_b32_e32 v71, v2
	v_lshlrev_b64 v[70:71], 12, v[70:71]
	v_mov_b32_e32 v69, v2
	v_lshl_add_u64 v[72:73], s[10:11], 0, v[70:71]
	v_lshlrev_b64 v[70:71], 12, v[68:69]
	s_andn2_saveexec_b64 s[16:17], s[16:17]
	v_ashrrev_i32_e32 v69, 31, v68
	v_lshlrev_b64 v[70:71], 12, v[68:69]
	v_lshl_add_u64 v[72:73], s[30:31], 0, v[70:71]
	s_or_b64 exec, exec, s[16:17]
	v_lshl_add_u64 v[80:81], v[72:73], 0, v[144:145]
	global_load_dwordx4 v[72:75], v[80:81], off
	global_load_dwordx4 v[76:79], v[80:81], off offset:16
	global_load_dwordx4 v[216:219], v[80:81], off offset:512
	global_load_dwordx4 v[220:223], v[80:81], off offset:528
	v_lshl_add_u64 v[70:71], s[30:31], 0, v[70:71]
	v_lshl_add_u64 v[82:83], v[70:71], 0, v[144:145]
	s_waitcnt vmcnt(3)
	v_pk_fma_f32 v[66:67], v[66:67], 0.5, v[74:75] op_sel_hi:[1,0,1]
	v_pk_fma_f32 v[64:65], v[64:65], 0.5, v[72:73] op_sel_hi:[1,0,1]
	s_waitcnt vmcnt(2)
	v_pk_fma_f32 v[62:63], v[62:63], 0.5, v[78:79] op_sel_hi:[1,0,1]
	v_pk_fma_f32 v[60:61], v[60:61], 0.5, v[76:77] op_sel_hi:[1,0,1]
	global_store_dwordx4 v[82:83], v[64:67], off
	global_store_dwordx4 v[82:83], v[60:63], off offset:16
	s_nop 0
	s_nop 0
	v_mul_f32_e32 v65, v65, v65
	v_mul_f32_e32 v67, v67, v67
	v_mul_f32_e32 v61, v61, v61
	v_fmac_f32_e32 v65, v64, v64
	v_fmac_f32_e32 v67, v66, v66
	v_mul_f32_e32 v63, v63, v63
	v_fmac_f32_e32 v61, v60, v60
	v_add_f32_e32 v60, v65, v67
	v_fmac_f32_e32 v63, v62, v62
	v_add_f32_e32 v60, v61, v60
	v_add_f32_e32 v64, v63, v60
	s_waitcnt vmcnt(3)
	v_pk_fma_f32 v[58:59], v[58:59], 0.5, v[218:219] op_sel_hi:[1,0,1]
	v_pk_fma_f32 v[56:57], v[56:57], 0.5, v[216:217] op_sel_hi:[1,0,1]
	s_waitcnt vmcnt(2)
	v_pk_fma_f32 v[60:61], v[52:53], 0.5, v[220:221] op_sel_hi:[1,0,1]
	v_mul_f32_e32 v52, v57, v57
	v_mul_f32_e32 v53, v59, v59
	v_pk_fma_f32 v[62:63], v[54:55], 0.5, v[222:223] op_sel_hi:[1,0,1]
	v_mul_f32_e32 v54, v61, v61
	v_fmac_f32_e32 v52, v56, v56
	v_fmac_f32_e32 v53, v58, v58
	v_mul_f32_e32 v55, v63, v63
	v_fmac_f32_e32 v54, v60, v60
	v_add_f32_e32 v52, v52, v53
	v_add_f32_e32 v52, v54, v52
	v_fmac_f32_e32 v55, v62, v62
	v_add_f32_e32 v52, v55, v52
	v_add_f32_e32 v52, v64, v52
	ds_bpermute_b32 v53, v3, v52
	global_store_dwordx4 v[82:83], v[56:59], off offset:512
	global_store_dwordx4 v[82:83], v[60:63], off offset:528
	s_waitcnt lgkmcnt(0)
	v_add_f32_e32 v52, v52, v53
	ds_bpermute_b32 v53, v122, v52
	s_and_saveexec_b64 s[16:17], s[4:5]
	s_cbranch_execz .LBB0_1654
	s_waitcnt lgkmcnt(0)
	v_add_f32_e32 v54, v52, v53
	v_lshl_add_u64 v[52:53], v[68:69], 2, s[20:21]
	v_mov_b32_e32 v240, v52
	v_mov_b32_e32 v241, v53
	v_mov_b32_e32 v242, v54
.LBB0_1654:
	s_or_b64 exec, exec, s[16:17]
	s_waitcnt lgkmcnt(0)
	v_add_u32_e32 v52, 0x90, v142
	v_cmp_lt_i32_e32 vcc, s69, v142
	s_and_saveexec_b64 s[16:17], vcc
	s_xor_b64 s[16:17], exec, s[16:17]
	v_add_u32_e32 v54, 0xffff8090, v142
	v_mov_b32_e32 v55, v2
	v_lshlrev_b64 v[54:55], 12, v[54:55]
	v_mov_b32_e32 v53, v2
	v_lshl_add_u64 v[56:57], s[10:11], 0, v[54:55]
	v_lshlrev_b64 v[54:55], 12, v[52:53]
	s_andn2_saveexec_b64 s[16:17], s[16:17]
	v_ashrrev_i32_e32 v53, 31, v52
	v_lshlrev_b64 v[54:55], 12, v[52:53]
	v_lshl_add_u64 v[56:57], s[30:31], 0, v[54:55]
	s_or_b64 exec, exec, s[16:17]
	v_lshl_add_u64 v[64:65], v[56:57], 0, v[144:145]
	global_load_dwordx4 v[56:59], v[64:65], off
	global_load_dwordx4 v[60:63], v[64:65], off offset:16
	global_load_dwordx4 v[216:219], v[64:65], off offset:512
	global_load_dwordx4 v[220:223], v[64:65], off offset:528
	v_lshl_add_u64 v[54:55], s[30:31], 0, v[54:55]
	v_lshl_add_u64 v[66:67], v[54:55], 0, v[144:145]
	s_waitcnt vmcnt(3)
	v_pk_fma_f32 v[50:51], v[50:51], 0.5, v[58:59] op_sel_hi:[1,0,1]
	v_pk_fma_f32 v[48:49], v[48:49], 0.5, v[56:57] op_sel_hi:[1,0,1]
	s_waitcnt vmcnt(2)
	v_pk_fma_f32 v[46:47], v[46:47], 0.5, v[62:63] op_sel_hi:[1,0,1]
	v_pk_fma_f32 v[44:45], v[44:45], 0.5, v[60:61] op_sel_hi:[1,0,1]
	global_store_dwordx4 v[66:67], v[48:51], off
	global_store_dwordx4 v[66:67], v[44:47], off offset:16
	s_nop 0
	s_nop 0
	v_mul_f32_e32 v49, v49, v49
	v_mul_f32_e32 v51, v51, v51
	v_mul_f32_e32 v45, v45, v45
	v_fmac_f32_e32 v49, v48, v48
	v_fmac_f32_e32 v51, v50, v50
	v_mul_f32_e32 v47, v47, v47
	v_fmac_f32_e32 v45, v44, v44
	v_add_f32_e32 v44, v49, v51
	v_fmac_f32_e32 v47, v46, v46
	v_add_f32_e32 v44, v45, v44
	v_add_f32_e32 v48, v47, v44
	s_waitcnt vmcnt(3)
	v_pk_fma_f32 v[42:43], v[42:43], 0.5, v[218:219] op_sel_hi:[1,0,1]
	v_pk_fma_f32 v[40:41], v[40:41], 0.5, v[216:217] op_sel_hi:[1,0,1]
	s_waitcnt vmcnt(2)
	v_pk_fma_f32 v[44:45], v[36:37], 0.5, v[220:221] op_sel_hi:[1,0,1]
	v_mul_f32_e32 v36, v41, v41
	v_mul_f32_e32 v37, v43, v43
	v_pk_fma_f32 v[46:47], v[38:39], 0.5, v[222:223] op_sel_hi:[1,0,1]
	v_mul_f32_e32 v38, v45, v45
	v_fmac_f32_e32 v36, v40, v40
	v_fmac_f32_e32 v37, v42, v42
	v_mul_f32_e32 v39, v47, v47
	v_fmac_f32_e32 v38, v44, v44
	v_add_f32_e32 v36, v36, v37
	v_add_f32_e32 v36, v38, v36
	v_fmac_f32_e32 v39, v46, v46
	v_add_f32_e32 v36, v39, v36
	v_add_f32_e32 v36, v48, v36
	ds_bpermute_b32 v37, v3, v36
	global_store_dwordx4 v[66:67], v[40:43], off offset:512
	global_store_dwordx4 v[66:67], v[44:47], off offset:528
	s_waitcnt lgkmcnt(0)
	v_add_f32_e32 v36, v36, v37
	ds_bpermute_b32 v37, v122, v36
	s_and_saveexec_b64 s[16:17], s[4:5]
	s_cbranch_execz .LBB0_1660
	s_waitcnt lgkmcnt(0)
	v_add_f32_e32 v38, v36, v37
	v_lshl_add_u64 v[36:37], v[52:53], 2, s[20:21]
	v_mov_b32_e32 v244, v36
	v_mov_b32_e32 v245, v37
	v_mov_b32_e32 v246, v38
; __device__ __forceinline__ u32x4 pack8(f32x4 a, f32x4 b) { u32x4 w; w.x = pk2(a[0], a[1]); w.y = pk2(a[2], a[3]); w.z = pk2(b[0], b[1]); w.w = pk2(b[2], b[3]); return w; }
; __device__ __forceinline__ float dot8(f32x4 a, f32x4 b) { return (a[0] * a[0] + a[1] * a[1]) + (a[2] * a[2] + a[3] * a[3]) + (b[0] * b[0] + b[1] * b[1]) + (b[2] * b[2] + b[3] * b[3]); }
; __device__ __forceinline__ float red_fq(float s) { s += __shfl_xor(s, 16); s += __shfl_xor(s, 32); return s; }
;     __device__ __forceinline__ void operator()(AccRef acc, const Unit& u, int wr, int wc, int fr, int fq) const {
;     ...
;             const float* rp = (row < MP) ? res0 + (size_t)row * DM : res1 + (size_t)(row - MP) * DM;
;             float s = 0.f;
;             _Pragma("unroll") for (int bj = 0; bj < 2; ++bj) { const int col = col0 + bj * 128;
;                 f32x4 v0 = *(const f32x4*)(rp + col) + acc[ai][bj][m][0] * scale, v1 = *(const f32x4*)(rp + col + 4) + acc[ai][bj][m][1] * scale;
;                 *(f32x4*)(out + (size_t)row * DM + col) = v0; *(f32x4*)(out + (size_t)row * DM + col + 4) = v1;
;                 if (WB) *(u32x4*)(ob + (size_t)row * DM + col) = pack8(v0, v1);
;                 s += dot8(v0, v1); }
;             s = red_fq(s); if (fq == 0) unsafeAtomicAdd(ss + row, s);
.LBB0_1660:
	s_or_b64 exec, exec, s[16:17]
	s_waitcnt lgkmcnt(0)
	v_add_u32_e32 v36, 0xa0, v142
	v_cmp_lt_i32_e32 vcc, s70, v142
	s_and_saveexec_b64 s[16:17], vcc
	s_xor_b64 s[16:17], exec, s[16:17]
	v_add_u32_e32 v38, 0xffff80a0, v142
	v_mov_b32_e32 v39, v2
	v_lshlrev_b64 v[38:39], 12, v[38:39]
	v_mov_b32_e32 v37, v2
	v_lshl_add_u64 v[40:41], s[10:11], 0, v[38:39]
	v_lshlrev_b64 v[38:39], 12, v[36:37]
	s_andn2_saveexec_b64 s[16:17], s[16:17]
	v_ashrrev_i32_e32 v37, 31, v36
	v_lshlrev_b64 v[38:39], 12, v[36:37]
	v_lshl_add_u64 v[40:41], s[30:31], 0, v[38:39]
	s_or_b64 exec, exec, s[16:17]
	v_lshl_add_u64 v[48:49], v[40:41], 0, v[144:145]
	global_load_dwordx4 v[40:43], v[48:49], off
	global_load_dwordx4 v[44:47], v[48:49], off offset:16
	global_load_dwordx4 v[216:219], v[48:49], off offset:512
	global_load_dwordx4 v[220:223], v[48:49], off offset:528
	v_lshl_add_u64 v[38:39], s[30:31], 0, v[38:39]
	v_lshl_add_u64 v[50:51], v[38:39], 0, v[144:145]
	s_waitcnt vmcnt(3)
	v_pk_fma_f32 v[34:35], v[34:35], 0.5, v[42:43] op_sel_hi:[1,0,1]
	v_pk_fma_f32 v[32:33], v[32:33], 0.5, v[40:41] op_sel_hi:[1,0,1]
	s_waitcnt vmcnt(2)
	v_pk_fma_f32 v[30:31], v[30:31], 0.5, v[46:47] op_sel_hi:[1,0,1]
	v_pk_fma_f32 v[28:29], v[28:29], 0.5, v[44:45] op_sel_hi:[1,0,1]
	global_store_dwordx4 v[50:51], v[32:35], off
	global_store_dwordx4 v[50:51], v[28:31], off offset:16
	s_nop 0
	s_nop 0
	v_mul_f32_e32 v33, v33, v33
	v_mul_f32_e32 v35, v35, v35
	v_mul_f32_e32 v29, v29, v29
	v_fmac_f32_e32 v33, v32, v32
	v_fmac_f32_e32 v35, v34, v34
	v_mul_f32_e32 v31, v31, v31
	v_fmac_f32_e32 v29, v28, v28
	v_add_f32_e32 v28, v33, v35
	v_fmac_f32_e32 v31, v30, v30
	v_add_f32_e32 v28, v29, v28
	v_add_f32_e32 v32, v31, v28
	s_waitcnt vmcnt(3)
	v_pk_fma_f32 v[26:27], v[26:27], 0.5, v[218:219] op_sel_hi:[1,0,1]
	v_pk_fma_f32 v[24:25], v[24:25], 0.5, v[216:217] op_sel_hi:[1,0,1]
	s_waitcnt vmcnt(2)
	v_pk_fma_f32 v[28:29], v[20:21], 0.5, v[220:221] op_sel_hi:[1,0,1]
	v_mul_f32_e32 v20, v25, v25
	v_mul_f32_e32 v21, v27, v27
	v_pk_fma_f32 v[30:31], v[22:23], 0.5, v[222:223] op_sel_hi:[1,0,1]
	v_mul_f32_e32 v22, v29, v29
	v_fmac_f32_e32 v20, v24, v24
	v_fmac_f32_e32 v21, v26, v26
	v_mul_f32_e32 v23, v31, v31
	v_fmac_f32_e32 v22, v28, v28
	v_add_f32_e32 v20, v20, v21
	v_add_f32_e32 v20, v22, v20
	v_fmac_f32_e32 v23, v30, v30
	v_add_f32_e32 v20, v23, v20
	v_add_f32_e32 v20, v32, v20
	ds_bpermute_b32 v21, v3, v20
	global_store_dwordx4 v[50:51], v[24:27], off offset:512
	global_store_dwordx4 v[50:51], v[28:31], off offset:528
	s_waitcnt lgkmcnt(0)
	v_add_f32_e32 v20, v20, v21
	ds_bpermute_b32 v21, v122, v20
	s_and_saveexec_b64 s[16:17], s[4:5]
	s_cbranch_execz .LBB0_1666
	s_waitcnt lgkmcnt(0)
	v_add_f32_e32 v22, v20, v21
	v_lshl_add_u64 v[20:21], v[36:37], 2, s[20:21]
	v_mov_b32_e32 v248, v20
	v_mov_b32_e32 v249, v21
	v_mov_b32_e32 v250, v22
.LBB0_1666:
	s_or_b64 exec, exec, s[16:17]
	s_waitcnt lgkmcnt(0)
	v_add_u32_e32 v20, 0xb0, v142
	v_cmp_lt_i32_e32 vcc, s71, v142
	s_and_saveexec_b64 s[16:17], vcc
	s_xor_b64 s[16:17], exec, s[16:17]
	v_add_u32_e32 v22, 0xffff80b0, v142
	v_mov_b32_e32 v23, v2
	v_lshlrev_b64 v[22:23], 12, v[22:23]
	v_mov_b32_e32 v21, v2
	v_lshl_add_u64 v[24:25], s[10:11], 0, v[22:23]
	v_lshlrev_b64 v[22:23], 12, v[20:21]
	s_andn2_saveexec_b64 s[16:17], s[16:17]
	v_ashrrev_i32_e32 v21, 31, v20
	v_lshlrev_b64 v[22:23], 12, v[20:21]
	v_lshl_add_u64 v[24:25], s[30:31], 0, v[22:23]
	s_or_b64 exec, exec, s[16:17]
	v_lshl_add_u64 v[32:33], v[24:25], 0, v[144:145]
	global_load_dwordx4 v[24:27], v[32:33], off
	global_load_dwordx4 v[28:31], v[32:33], off offset:16
	global_load_dwordx4 v[216:219], v[32:33], off offset:512
	global_load_dwordx4 v[220:223], v[32:33], off offset:528
	v_lshl_add_u64 v[22:23], s[30:31], 0, v[22:23]
	v_lshl_add_u64 v[34:35], v[22:23], 0, v[144:145]
	s_waitcnt vmcnt(3)
	v_pk_fma_f32 v[18:19], v[18:19], 0.5, v[26:27] op_sel_hi:[1,0,1]
	v_pk_fma_f32 v[16:17], v[16:17], 0.5, v[24:25] op_sel_hi:[1,0,1]
	s_waitcnt vmcnt(2)
	v_pk_fma_f32 v[14:15], v[14:15], 0.5, v[30:31] op_sel_hi:[1,0,1]
	v_pk_fma_f32 v[12:13], v[12:13], 0.5, v[28:29] op_sel_hi:[1,0,1]
	global_store_dwordx4 v[34:35], v[16:19], off
	global_store_dwordx4 v[34:35], v[12:15], off offset:16
	s_nop 0
	s_nop 0
	v_mul_f32_e32 v17, v17, v17
	v_mul_f32_e32 v19, v19, v19
	v_mul_f32_e32 v13, v13, v13
	v_fmac_f32_e32 v17, v16, v16
	v_fmac_f32_e32 v19, v18, v18
	v_mul_f32_e32 v15, v15, v15
	v_fmac_f32_e32 v13, v12, v12
	v_add_f32_e32 v12, v17, v19
	v_fmac_f32_e32 v15, v14, v14
	v_add_f32_e32 v12, v13, v12
	v_add_f32_e32 v16, v15, v12
	s_waitcnt vmcnt(3)
	v_pk_fma_f32 v[10:11], v[10:11], 0.5, v[218:219] op_sel_hi:[1,0,1]
	v_pk_fma_f32 v[8:9], v[8:9], 0.5, v[216:217] op_sel_hi:[1,0,1]
	s_waitcnt vmcnt(2)
	v_pk_fma_f32 v[12:13], v[4:5], 0.5, v[220:221] op_sel_hi:[1,0,1]
	v_mul_f32_e32 v4, v9, v9
	v_mul_f32_e32 v5, v11, v11
	v_pk_fma_f32 v[14:15], v[6:7], 0.5, v[222:223] op_sel_hi:[1,0,1]
	v_mul_f32_e32 v6, v13, v13
	v_fmac_f32_e32 v4, v8, v8
	v_fmac_f32_e32 v5, v10, v10
	v_mul_f32_e32 v7, v15, v15
	v_fmac_f32_e32 v6, v12, v12
	v_add_f32_e32 v4, v4, v5
	v_add_f32_e32 v4, v6, v4
	v_fmac_f32_e32 v7, v14, v14
	v_add_f32_e32 v4, v7, v4
	v_add_f32_e32 v4, v16, v4
	ds_bpermute_b32 v3, v3, v4
	global_store_dwordx4 v[34:35], v[8:11], off offset:512
	global_store_dwordx4 v[34:35], v[12:15], off offset:528
	s_waitcnt lgkmcnt(0)
	v_add_f32_e32 v3, v4, v3
	ds_bpermute_b32 v4, v122, v3
	s_and_saveexec_b64 s[16:17], s[4:5]
	s_cbranch_execz .LBB0_1672
	s_waitcnt lgkmcnt(0)
	v_add_f32_e32 v3, v3, v4
	v_lshl_add_u64 v[4:5], v[20:21], 2, s[20:21]
	global_atomic_add_f32 v[4:5], v3, off
	global_atomic_add_f32 v[224:225], v226, off
	global_atomic_add_f32 v[228:229], v230, off
	global_atomic_add_f32 v[232:233], v234, off
	global_atomic_add_f32 v[236:237], v238, off
	global_atomic_add_f32 v[240:241], v242, off
	global_atomic_add_f32 v[244:245], v246, off
	global_atomic_add_f32 v[248:249], v250, off
